# GEMM K-loops: MFMA-block closing barrier issued one MFMA early, that half at priority 1 around it so its last MFMA issues first; stacked on stack18
# speedup vs baseline: 1.0068x; 1.0001x over previous
; #define PG8_STAGE(bufoff, gbase, voff) do { _Pragma("unroll") for (int _i = 0; _i < 2; ++_i) \
;         __builtin_amdgcn_global_load_lds((const unsigned*)((const char*)(gbase) + (voff)[_i]), (PG8_LAS unsigned*)(lds + (bufoff) + ldsw + _i * 8192), 16, 0, 0); } while (0)
; #define PG8_LDA(dst, b, h) do { _Pragma("unroll") for (int m = 0; m < 4; ++m) _Pragma("unroll") for (int k = 0; k < 2; ++k) dst[m][k] = *(const PG8_LAS bf16x8*)(lds + PG8_SA(b, h) + aoff + m * 2048 + k * 1024); } while (0)
; #define PG8_LDB(dst, b, h) do { _Pragma("unroll") for (int n = 0; n < 2; ++n) _Pragma("unroll") for (int k = 0; k < 2; ++k) dst[n][k] = *(const PG8_LAS bf16x8*)(lds + PG8_SB(b, h) + boff + n * 2048 + k * 1024); } while (0)
; #define PG8_MMA(ai, bj, At, Bt) do { __builtin_amdgcn_s_setprio(1); _Pragma("unroll") for (int m = 0; m < 4; ++m) _Pragma("unroll") for (int n = 0; n < 2; ++n) _Pragma("unroll") for (int k = 0; k < 2; ++k) \
;         acc[ai][bj][m][n] = __builtin_amdgcn_mfma_f32_16x16x32_bf16(Bt[n][k], At[m][k], acc[ai][bj][m][n], 0, 0, 0); __builtin_amdgcn_s_setprio(0); } while (0)
; #define PG8_WAIT_V(n) asm volatile("s_waitcnt vmcnt(" #n ")" ::: "memory")
; #define PG8_WAIT_L(n) asm volatile("s_waitcnt lgkmcnt(" #n ")" ::: "memory")
; #define PG8_BAR __builtin_amdgcn_s_barrier()
; #define PG8_SCHED __builtin_amdgcn_sched_barrier(0)
; template <class Epi, class Sched, bool ALIGN_EPI = false, bool SP2 = false>
; __device__ __forceinline__ void gemm_phase(PG8_LAS unsigned char* lds, const Gemm g, const Sched& S, const Epi& E) {
;     ...
;         for (int t = 0; t < nt; t += 2) {
;             const bool last = (t == nt - 2);
;             const char* a1 = cA + (size_t)(t + 1) * kstep;
;             const char* a2 = last ? nA : cA + (size_t)(t + 2) * kstep; const char* b2 = last ? nB : cB + (size_t)(t + 2) * kstep;
;             const char* a3 = a2 + kstep; const char* b3 = b2 + kstep;
;             if (last && has_next) S.a_ready(nxt);
;             if constexpr (SP2) {
;             PG8_LDB(B0, 0, 0); PG8_LDB(B1, 0, 1); PG8_SCHED; PG8_LDA(At, 0, 0); PG8_STAGE(PG8_SA(1, 1), a1 + hstep, voffA);
;             PG8_WAIT_V(8); PG8_WAIT_L(0); PG8_BAR; PG8_MMA(0, 0, At, B0); PG8_MMA(0, 1, At, B1); PG8_BAR; PG8_SCHED;
;             PG8_LDA(At, 0, 1); PG8_STAGE(PG8_SB(0, 0), b2, voffB); PG8_STAGE(PG8_SB(0, 1), b2 + hstep, voffB); PG8_STAGE(PG8_SA(0, 0), a2, voffA);
.LBB0_164:
	s_add_u32 s58, s72, 0xfffc0080
	s_addc_u32 s59, s73, -1
	s_add_i32 s84, 0, 0x10000
	s_cmp_eq_u32 s94, 12
	s_cselect_b32 s65, s36, s59
	s_cselect_b32 s64, s37, s58
	v_add_u32_e32 v140, s84, v146
	s_cselect_b32 s59, s51, s93
	s_cselect_b32 s58, s53, s92
	s_add_i32 s96, 0, 0x14000
	ds_read_b128 v[142:145], v140
	ds_read_b128 v[150:153], v140 offset:1024
	ds_read_b128 v[154:157], v140 offset:2048
	ds_read_b128 v[158:161], v140 offset:3072
	v_add_u32_e32 v140, s96, v146
	ds_read_b128 v[162:165], v140
	ds_read_b128 v[166:169], v140 offset:1024
	ds_read_b128 v[170:173], v140 offset:2048
	ds_read_b128 v[174:177], v140 offset:3072
	v_lshl_add_u64 v[186:187], s[72:73], 0, v[136:137]
	s_add_i32 m0, s19, 0xc000
	ds_read_b128 v[178:181], v148
	ds_read_b128 v[182:185], v148 offset:1024
	ds_read_b128 v[190:193], v148 offset:2048
	ds_read_b128 v[194:197], v148 offset:3072
	ds_read_b128 v[198:201], v148 offset:4096
	ds_read_b128 v[202:205], v148 offset:5120
	ds_read_b128 v[206:209], v148 offset:6144
	ds_read_b128 v[228:231], v148 offset:7168
	global_load_lds_dwordx4 v[186:187], off
	v_lshl_add_u64 v[186:187], s[72:73], 0, v[138:139]
	s_add_i32 m0, s19, 0xe000
	s_nop 0
	global_load_lds_dwordx4 v[186:187], off
	s_waitcnt vmcnt(8)
	s_waitcnt lgkmcnt(0)
	s_barrier
	s_waitcnt lgkmcnt(0)
	v_mfma_f32_16x16x32_bf16 v[124:127], v[142:145], v[178:181], v[124:127]
	v_mfma_f32_16x16x32_bf16 v[120:123], v[154:157], v[178:181], v[120:123]
	v_mfma_f32_16x16x32_bf16 v[116:119], v[142:145], v[190:193], v[116:119]
	v_mfma_f32_16x16x32_bf16 v[112:115], v[154:157], v[190:193], v[112:115]
	v_mfma_f32_16x16x32_bf16 v[108:111], v[142:145], v[198:201], v[108:111]
	v_mfma_f32_16x16x32_bf16 v[104:107], v[154:157], v[198:201], v[104:107]
	v_mfma_f32_16x16x32_bf16 v[100:103], v[142:145], v[206:209], v[100:103]
	v_mfma_f32_16x16x32_bf16 v[96:99], v[154:157], v[206:209], v[96:99]
	v_mfma_f32_16x16x32_bf16 v[124:127], v[150:153], v[182:185], v[124:127]
	v_mfma_f32_16x16x32_bf16 v[120:123], v[158:161], v[182:185], v[120:123]
	v_mfma_f32_16x16x32_bf16 v[116:119], v[150:153], v[194:197], v[116:119]
	v_mfma_f32_16x16x32_bf16 v[112:115], v[158:161], v[194:197], v[112:115]
	v_mfma_f32_16x16x32_bf16 v[108:111], v[150:153], v[202:205], v[108:111]
	v_mfma_f32_16x16x32_bf16 v[104:107], v[158:161], v[202:205], v[104:107]
	v_mfma_f32_16x16x32_bf16 v[100:103], v[150:153], v[228:231], v[100:103]
	v_mfma_f32_16x16x32_bf16 v[96:99], v[158:161], v[228:231], v[96:99]
	v_mfma_f32_16x16x32_bf16 v[92:95], v[162:165], v[178:181], v[92:95]
	v_mfma_f32_16x16x32_bf16 v[88:91], v[170:173], v[178:181], v[88:91]
	v_mfma_f32_16x16x32_bf16 v[84:87], v[162:165], v[190:193], v[84:87]
	v_mfma_f32_16x16x32_bf16 v[80:83], v[170:173], v[190:193], v[80:83]
	v_mfma_f32_16x16x32_bf16 v[76:79], v[162:165], v[198:201], v[76:79]
	v_mfma_f32_16x16x32_bf16 v[72:75], v[170:173], v[198:201], v[72:75]
	v_mfma_f32_16x16x32_bf16 v[68:71], v[162:165], v[206:209], v[68:71]
	v_mfma_f32_16x16x32_bf16 v[64:67], v[170:173], v[206:209], v[64:67]
	v_mfma_f32_16x16x32_bf16 v[92:95], v[166:169], v[182:185], v[92:95]
	v_mfma_f32_16x16x32_bf16 v[88:91], v[174:177], v[182:185], v[88:91]
	v_mfma_f32_16x16x32_bf16 v[84:87], v[166:169], v[194:197], v[84:87]
	v_mfma_f32_16x16x32_bf16 v[80:83], v[174:177], v[194:197], v[80:83]
	s_setprio 1
	v_mfma_f32_16x16x32_bf16 v[76:79], v[166:169], v[202:205], v[76:79]
	v_mfma_f32_16x16x32_bf16 v[72:75], v[174:177], v[202:205], v[72:75]
	v_mfma_f32_16x16x32_bf16 v[68:71], v[166:169], v[228:231], v[68:71]
	s_barrier
	v_mfma_f32_16x16x32_bf16 v[64:67], v[174:177], v[228:231], v[64:67]
	s_setprio 0
	s_add_i32 s84, s84, s18
	v_lshl_add_u64 v[186:187], s[58:59], 0, v[128:129]
	s_mov_b32 m0, s84
	ds_read_b128 v[178:181], v148 offset:16384
	ds_read_b128 v[182:185], v148 offset:17408
	ds_read_b128 v[190:193], v148 offset:18432
	ds_read_b128 v[194:197], v148 offset:19456
	ds_read_b128 v[198:201], v148 offset:20480
	ds_read_b128 v[202:205], v148 offset:21504
	ds_read_b128 v[206:209], v148 offset:22528
	ds_read_b128 v[228:231], v148 offset:23552
	global_load_lds_dwordx4 v[186:187], off
	s_add_i32 m0, s84, 0x2000
	s_add_u32 s84, s58, 0x40000
	v_lshl_add_u64 v[188:189], s[58:59], 0, v[130:131]
	s_addc_u32 s85, s59, 0
	s_add_i32 s96, s96, s18
	global_load_lds_dwordx4 v[188:189], off
	v_lshl_add_u64 v[210:211], s[84:85], 0, v[128:129]
	s_mov_b32 m0, s96
	v_lshl_add_u64 v[232:233], s[64:65], 0, v[132:133]
	global_load_lds_dwordx4 v[210:211], off
	v_lshl_add_u64 v[210:211], s[84:85], 0, v[130:131]
	s_add_i32 m0, s96, 0x2000
	s_nop 0
	global_load_lds_dwordx4 v[210:211], off
	v_lshl_add_u64 v[210:211], s[64:65], 0, v[134:135]
	s_mov_b32 m0, s19
	s_nop 0
	global_load_lds_dwordx4 v[210:211], off
	s_mov_b32 m0, s20
	s_nop 0
	global_load_lds_dwordx4 v[232:233], off
	s_waitcnt vmcnt(8)
	s_waitcnt lgkmcnt(0)
	s_barrier
; #define PG8_STAGE(bufoff, gbase, voff) do { _Pragma("unroll") for (int _i = 0; _i < 2; ++_i) \
;         __builtin_amdgcn_global_load_lds((const unsigned*)((const char*)(gbase) + (voff)[_i]), (PG8_LAS unsigned*)(lds + (bufoff) + ldsw + _i * 8192), 16, 0, 0); } while (0)
; #define PG8_LDA(dst, b, h) do { _Pragma("unroll") for (int m = 0; m < 4; ++m) _Pragma("unroll") for (int k = 0; k < 2; ++k) dst[m][k] = *(const PG8_LAS bf16x8*)(lds + PG8_SA(b, h) + aoff + m * 2048 + k * 1024); } while (0)
; #define PG8_LDB(dst, b, h) do { _Pragma("unroll") for (int n = 0; n < 2; ++n) _Pragma("unroll") for (int k = 0; k < 2; ++k) dst[n][k] = *(const PG8_LAS bf16x8*)(lds + PG8_SB(b, h) + boff + n * 2048 + k * 1024); } while (0)
; #define PG8_MMA(ai, bj, At, Bt) do { __builtin_amdgcn_s_setprio(1); _Pragma("unroll") for (int m = 0; m < 4; ++m) _Pragma("unroll") for (int n = 0; n < 2; ++n) _Pragma("unroll") for (int k = 0; k < 2; ++k) \
;         acc[ai][bj][m][n] = __builtin_amdgcn_mfma_f32_16x16x32_bf16(Bt[n][k], At[m][k], acc[ai][bj][m][n], 0, 0, 0); __builtin_amdgcn_s_setprio(0); } while (0)
; #define PG8_WAIT_V(n) asm volatile("s_waitcnt vmcnt(" #n ")" ::: "memory")
; #define PG8_WAIT_L(n) asm volatile("s_waitcnt lgkmcnt(" #n ")" ::: "memory")
; #define PG8_BAR __builtin_amdgcn_s_barrier()
; #define PG8_SCHED __builtin_amdgcn_sched_barrier(0)
; template <class Epi, class Sched, bool ALIGN_EPI = false, bool SP2 = false>
; __device__ __forceinline__ void gemm_phase(PG8_LAS unsigned char* lds, const Gemm g, const Sched& S, const Epi& E) {
;     ...
;             PG8_WAIT_V(8); PG8_WAIT_L(0); PG8_BAR; PG8_MMA(1, 0, At, B0); PG8_MMA(1, 1, At, B1); PG8_BAR; PG8_SCHED;
;             PG8_LDB(B0, 1, 0); PG8_LDB(B1, 1, 1); PG8_SCHED; PG8_LDA(At, 1, 0); PG8_STAGE(PG8_SA(0, 1), a2 + hstep, voffA);
;             PG8_WAIT_V(8); PG8_WAIT_L(0); PG8_BAR; PG8_MMA(0, 0, At, B0); PG8_MMA(0, 1, At, B1); PG8_BAR; PG8_SCHED;
	s_waitcnt lgkmcnt(0)
	v_mfma_f32_16x16x32_bf16 v[60:63], v[142:145], v[178:181], v[60:63]
	v_mfma_f32_16x16x32_bf16 v[56:59], v[154:157], v[178:181], v[56:59]
	v_mfma_f32_16x16x32_bf16 v[52:55], v[142:145], v[190:193], v[52:55]
	v_mfma_f32_16x16x32_bf16 v[48:51], v[154:157], v[190:193], v[48:51]
	v_mfma_f32_16x16x32_bf16 v[44:47], v[142:145], v[198:201], v[44:47]
	v_mfma_f32_16x16x32_bf16 v[40:43], v[154:157], v[198:201], v[40:43]
	v_mfma_f32_16x16x32_bf16 v[36:39], v[142:145], v[206:209], v[36:39]
	v_mfma_f32_16x16x32_bf16 v[32:35], v[154:157], v[206:209], v[32:35]
	v_mfma_f32_16x16x32_bf16 v[60:63], v[150:153], v[182:185], v[60:63]
	v_mfma_f32_16x16x32_bf16 v[56:59], v[158:161], v[182:185], v[56:59]
	v_mfma_f32_16x16x32_bf16 v[52:55], v[150:153], v[194:197], v[52:55]
	v_mfma_f32_16x16x32_bf16 v[48:51], v[158:161], v[194:197], v[48:51]
	v_mfma_f32_16x16x32_bf16 v[44:47], v[150:153], v[202:205], v[44:47]
	v_mfma_f32_16x16x32_bf16 v[40:43], v[158:161], v[202:205], v[40:43]
	v_mfma_f32_16x16x32_bf16 v[36:39], v[150:153], v[228:231], v[36:39]
	v_mfma_f32_16x16x32_bf16 v[32:35], v[158:161], v[228:231], v[32:35]
	v_mfma_f32_16x16x32_bf16 v[28:31], v[162:165], v[178:181], v[28:31]
	v_mfma_f32_16x16x32_bf16 v[24:27], v[170:173], v[178:181], v[24:27]
	v_mfma_f32_16x16x32_bf16 v[20:23], v[162:165], v[190:193], v[20:23]
	v_mfma_f32_16x16x32_bf16 v[16:19], v[170:173], v[190:193], v[16:19]
	v_mfma_f32_16x16x32_bf16 v[12:15], v[162:165], v[198:201], v[12:15]
	v_mfma_f32_16x16x32_bf16 v[8:11], v[170:173], v[198:201], v[8:11]
	v_mfma_f32_16x16x32_bf16 v[4:7], v[162:165], v[206:209], v[4:7]
	v_mfma_f32_16x16x32_bf16 v[0:3], v[170:173], v[206:209], v[0:3]
	v_mfma_f32_16x16x32_bf16 v[28:31], v[166:169], v[182:185], v[28:31]
	v_mfma_f32_16x16x32_bf16 v[24:27], v[174:177], v[182:185], v[24:27]
	v_mfma_f32_16x16x32_bf16 v[20:23], v[166:169], v[194:197], v[20:23]
	v_mfma_f32_16x16x32_bf16 v[16:19], v[174:177], v[194:197], v[16:19]
	s_setprio 1
	v_mfma_f32_16x16x32_bf16 v[12:15], v[166:169], v[202:205], v[12:15]
	v_mfma_f32_16x16x32_bf16 v[8:11], v[174:177], v[202:205], v[8:11]
	v_mfma_f32_16x16x32_bf16 v[4:7], v[166:169], v[228:231], v[4:7]
	s_barrier
	v_mfma_f32_16x16x32_bf16 v[0:3], v[174:177], v[228:231], v[0:3]
	s_setprio 0
	s_add_i32 s84, 0, 0x18000
	v_add_u32_e32 v140, s84, v146
	s_add_i32 s85, 0, 0x1c000
	ds_read_b128 v[142:145], v140
	ds_read_b128 v[150:153], v140 offset:1024
	ds_read_b128 v[154:157], v140 offset:2048
	ds_read_b128 v[158:161], v140 offset:3072
	v_add_u32_e32 v140, s85, v146
	ds_read_b128 v[162:165], v140
	ds_read_b128 v[166:169], v140 offset:1024
	ds_read_b128 v[170:173], v140 offset:2048
	ds_read_b128 v[174:177], v140 offset:3072
	s_add_u32 s64, s64, 0x40000
	s_addc_u32 s65, s65, 0
	s_mov_b32 m0, s21
	v_lshl_add_u64 v[234:235], s[64:65], 0, v[134:135]
	ds_read_b128 v[178:181], v148 offset:32768
	ds_read_b128 v[182:185], v148 offset:33792
	ds_read_b128 v[190:193], v148 offset:34816
	ds_read_b128 v[194:197], v148 offset:35840
	ds_read_b128 v[198:201], v148 offset:36864
	ds_read_b128 v[202:205], v148 offset:37888
	ds_read_b128 v[206:209], v148 offset:38912
	ds_read_b128 v[228:231], v148 offset:39936
	global_load_lds_dwordx4 v[234:235], off
	v_lshl_add_u64 v[234:235], s[64:65], 0, v[132:133]
	s_mov_b32 m0, s22
	s_nop 0
	global_load_lds_dwordx4 v[234:235], off
	s_waitcnt vmcnt(8)
	s_waitcnt lgkmcnt(0)
	s_barrier
	s_waitcnt lgkmcnt(0)
	v_mfma_f32_16x16x32_bf16 v[124:127], v[142:145], v[178:181], v[124:127]
	v_mfma_f32_16x16x32_bf16 v[120:123], v[154:157], v[178:181], v[120:123]
	v_mfma_f32_16x16x32_bf16 v[116:119], v[142:145], v[190:193], v[116:119]
	v_mfma_f32_16x16x32_bf16 v[112:115], v[154:157], v[190:193], v[112:115]
	v_mfma_f32_16x16x32_bf16 v[108:111], v[142:145], v[198:201], v[108:111]
	v_mfma_f32_16x16x32_bf16 v[104:107], v[154:157], v[198:201], v[104:107]
	v_mfma_f32_16x16x32_bf16 v[100:103], v[142:145], v[206:209], v[100:103]
	v_mfma_f32_16x16x32_bf16 v[96:99], v[154:157], v[206:209], v[96:99]
	v_mfma_f32_16x16x32_bf16 v[124:127], v[150:153], v[182:185], v[124:127]
	v_mfma_f32_16x16x32_bf16 v[120:123], v[158:161], v[182:185], v[120:123]
	v_mfma_f32_16x16x32_bf16 v[116:119], v[150:153], v[194:197], v[116:119]
	v_mfma_f32_16x16x32_bf16 v[112:115], v[158:161], v[194:197], v[112:115]
	v_mfma_f32_16x16x32_bf16 v[108:111], v[150:153], v[202:205], v[108:111]
	v_mfma_f32_16x16x32_bf16 v[104:107], v[158:161], v[202:205], v[104:107]
	v_mfma_f32_16x16x32_bf16 v[100:103], v[150:153], v[228:231], v[100:103]
	v_mfma_f32_16x16x32_bf16 v[96:99], v[158:161], v[228:231], v[96:99]
	v_mfma_f32_16x16x32_bf16 v[92:95], v[162:165], v[178:181], v[92:95]
	v_mfma_f32_16x16x32_bf16 v[88:91], v[170:173], v[178:181], v[88:91]
	v_mfma_f32_16x16x32_bf16 v[84:87], v[162:165], v[190:193], v[84:87]
	v_mfma_f32_16x16x32_bf16 v[80:83], v[170:173], v[190:193], v[80:83]
	v_mfma_f32_16x16x32_bf16 v[76:79], v[162:165], v[198:201], v[76:79]
	v_mfma_f32_16x16x32_bf16 v[72:75], v[170:173], v[198:201], v[72:75]
	v_mfma_f32_16x16x32_bf16 v[68:71], v[162:165], v[206:209], v[68:71]
	v_mfma_f32_16x16x32_bf16 v[64:67], v[170:173], v[206:209], v[64:67]
	v_mfma_f32_16x16x32_bf16 v[92:95], v[166:169], v[182:185], v[92:95]
	v_mfma_f32_16x16x32_bf16 v[88:91], v[174:177], v[182:185], v[88:91]
	v_mfma_f32_16x16x32_bf16 v[84:87], v[166:169], v[194:197], v[84:87]
	v_mfma_f32_16x16x32_bf16 v[80:83], v[174:177], v[194:197], v[80:83]
	s_setprio 1
	v_mfma_f32_16x16x32_bf16 v[76:79], v[166:169], v[202:205], v[76:79]
	v_mfma_f32_16x16x32_bf16 v[72:75], v[174:177], v[202:205], v[72:75]
	v_mfma_f32_16x16x32_bf16 v[68:71], v[166:169], v[228:231], v[68:71]
	s_barrier
; #define PG8_STAGE(bufoff, gbase, voff) do { _Pragma("unroll") for (int _i = 0; _i < 2; ++_i) \
;         __builtin_amdgcn_global_load_lds((const unsigned*)((const char*)(gbase) + (voff)[_i]), (PG8_LAS unsigned*)(lds + (bufoff) + ldsw + _i * 8192), 16, 0, 0); } while (0)
; #define PG8_LDA(dst, b, h) do { _Pragma("unroll") for (int m = 0; m < 4; ++m) _Pragma("unroll") for (int k = 0; k < 2; ++k) dst[m][k] = *(const PG8_LAS bf16x8*)(lds + PG8_SA(b, h) + aoff + m * 2048 + k * 1024); } while (0)
; #define PG8_MMA(ai, bj, At, Bt) do { __builtin_amdgcn_s_setprio(1); _Pragma("unroll") for (int m = 0; m < 4; ++m) _Pragma("unroll") for (int n = 0; n < 2; ++n) _Pragma("unroll") for (int k = 0; k < 2; ++k) \
;         acc[ai][bj][m][n] = __builtin_amdgcn_mfma_f32_16x16x32_bf16(Bt[n][k], At[m][k], acc[ai][bj][m][n], 0, 0, 0); __builtin_amdgcn_s_setprio(0); } while (0)
; #define PG8_WAIT_V(n) asm volatile("s_waitcnt vmcnt(" #n ")" ::: "memory")
; #define PG8_WAIT_L(n) asm volatile("s_waitcnt lgkmcnt(" #n ")" ::: "memory")
; #define PG8_BAR __builtin_amdgcn_s_barrier()
; #define PG8_SCHED __builtin_amdgcn_sched_barrier(0)
; template <class Epi, class Sched, bool ALIGN_EPI = false, bool SP2 = false>
; __device__ __forceinline__ void gemm_phase(PG8_LAS unsigned char* lds, const Gemm g, const Sched& S, const Epi& E) {
;     ...
;             PG8_LDA(At, 1, 1); PG8_STAGE(PG8_SB(1, 0), b3, voffB); PG8_STAGE(PG8_SB(1, 1), b3 + hstep, voffB); PG8_STAGE(PG8_SA(1, 0), a3, voffA);
;             PG8_WAIT_V(8); PG8_WAIT_L(0); PG8_BAR; PG8_MMA(1, 0, At, B0); PG8_MMA(1, 1, At, B1); PG8_BAR; PG8_SCHED;
;     ...
;         if constexpr (ALIGN_EPI) { if (wr == 0) PG8_BAR; }
	v_mfma_f32_16x16x32_bf16 v[64:67], v[174:177], v[228:231], v[64:67]
	s_setprio 0
	s_add_i32 s64, s84, s18
	v_lshl_add_u64 v[186:187], v[186:187], 0, s[90:91]
	s_mov_b32 m0, s64
	ds_read_b128 v[178:181], v148 offset:49152
	ds_read_b128 v[182:185], v148 offset:50176
	ds_read_b128 v[190:193], v148 offset:51200
	ds_read_b128 v[194:197], v148 offset:52224
	ds_read_b128 v[198:201], v148 offset:53248
	ds_read_b128 v[202:205], v148 offset:54272
	ds_read_b128 v[206:209], v148 offset:55296
	ds_read_b128 v[228:231], v148 offset:56320
	global_load_lds_dwordx4 v[186:187], off
	s_add_i32 m0, s64, 0x2000
	s_add_u32 s58, s58, 0x40080
	v_lshl_add_u64 v[186:187], v[188:189], 0, s[90:91]
	s_addc_u32 s59, s59, 0
	s_add_i32 s64, s85, s18
	global_load_lds_dwordx4 v[186:187], off
	v_lshl_add_u64 v[186:187], s[58:59], 0, v[128:129]
	s_mov_b32 m0, s64
	s_nop 0
	global_load_lds_dwordx4 v[186:187], off
	v_lshl_add_u64 v[186:187], s[58:59], 0, v[130:131]
	s_add_i32 m0, s64, 0x2000
	s_nop 0
	global_load_lds_dwordx4 v[186:187], off
	v_lshl_add_u64 v[186:187], v[210:211], 0, s[90:91]
	s_mov_b32 m0, s28
	s_nop 0
	global_load_lds_dwordx4 v[186:187], off
	v_lshl_add_u64 v[186:187], v[232:233], 0, s[90:91]
	s_mov_b32 m0, s29
	s_nop 0
	global_load_lds_dwordx4 v[186:187], off
	s_waitcnt vmcnt(8)
	s_waitcnt lgkmcnt(0)
	s_barrier
	s_waitcnt lgkmcnt(0)
	v_mfma_f32_16x16x32_bf16 v[60:63], v[142:145], v[178:181], v[60:63]
	v_mfma_f32_16x16x32_bf16 v[56:59], v[154:157], v[178:181], v[56:59]
	v_mfma_f32_16x16x32_bf16 v[52:55], v[142:145], v[190:193], v[52:55]
	v_mfma_f32_16x16x32_bf16 v[48:51], v[154:157], v[190:193], v[48:51]
	v_mfma_f32_16x16x32_bf16 v[44:47], v[142:145], v[198:201], v[44:47]
	v_mfma_f32_16x16x32_bf16 v[40:43], v[154:157], v[198:201], v[40:43]
	v_mfma_f32_16x16x32_bf16 v[36:39], v[142:145], v[206:209], v[36:39]
	v_mfma_f32_16x16x32_bf16 v[32:35], v[154:157], v[206:209], v[32:35]
	v_mfma_f32_16x16x32_bf16 v[60:63], v[150:153], v[182:185], v[60:63]
	v_mfma_f32_16x16x32_bf16 v[56:59], v[158:161], v[182:185], v[56:59]
	v_mfma_f32_16x16x32_bf16 v[52:55], v[150:153], v[194:197], v[52:55]
	v_mfma_f32_16x16x32_bf16 v[48:51], v[158:161], v[194:197], v[48:51]
	v_mfma_f32_16x16x32_bf16 v[44:47], v[150:153], v[202:205], v[44:47]
	v_mfma_f32_16x16x32_bf16 v[40:43], v[158:161], v[202:205], v[40:43]
	v_mfma_f32_16x16x32_bf16 v[36:39], v[150:153], v[228:231], v[36:39]
	v_mfma_f32_16x16x32_bf16 v[32:35], v[158:161], v[228:231], v[32:35]
	v_mfma_f32_16x16x32_bf16 v[28:31], v[162:165], v[178:181], v[28:31]
	v_mfma_f32_16x16x32_bf16 v[24:27], v[170:173], v[178:181], v[24:27]
	v_mfma_f32_16x16x32_bf16 v[20:23], v[162:165], v[190:193], v[20:23]
	v_mfma_f32_16x16x32_bf16 v[16:19], v[170:173], v[190:193], v[16:19]
	v_mfma_f32_16x16x32_bf16 v[12:15], v[162:165], v[198:201], v[12:15]
	v_mfma_f32_16x16x32_bf16 v[8:11], v[170:173], v[198:201], v[8:11]
	v_mfma_f32_16x16x32_bf16 v[4:7], v[162:165], v[206:209], v[4:7]
	v_mfma_f32_16x16x32_bf16 v[0:3], v[170:173], v[206:209], v[0:3]
	v_mfma_f32_16x16x32_bf16 v[28:31], v[166:169], v[182:185], v[28:31]
	v_mfma_f32_16x16x32_bf16 v[24:27], v[174:177], v[182:185], v[24:27]
	v_mfma_f32_16x16x32_bf16 v[20:23], v[166:169], v[194:197], v[20:23]
	v_mfma_f32_16x16x32_bf16 v[16:19], v[174:177], v[194:197], v[16:19]
	s_setprio 1
	v_mfma_f32_16x16x32_bf16 v[12:15], v[166:169], v[202:205], v[12:15]
	v_mfma_f32_16x16x32_bf16 v[8:11], v[174:177], v[202:205], v[8:11]
	v_mfma_f32_16x16x32_bf16 v[4:7], v[166:169], v[228:231], v[4:7]
	s_barrier
	v_mfma_f32_16x16x32_bf16 v[0:3], v[174:177], v[228:231], v[0:3]
	s_setprio 0
	s_add_i32 s94, s94, 2
	s_add_u32 s72, s72, 0x100
	s_addc_u32 s73, s73, 0
	s_add_u32 s92, s92, 0x100
	s_addc_u32 s93, s93, 0
	s_cmp_gt_u32 s94, 13
	s_cbranch_scc0 .LBB0_164
	s_and_b64 vcc, exec, s[48:49]
	s_cbranch_vccz .LBB0_167
	s_barrier

; #define PG8_STAGE(bufoff, gbase, voff) do { _Pragma("unroll") for (int _i = 0; _i < 2; ++_i) \
;         __builtin_amdgcn_global_load_lds((const unsigned*)((const char*)(gbase) + (voff)[_i]), (PG8_LAS unsigned*)(lds + (bufoff) + ldsw + _i * 8192), 16, 0, 0); } while (0)
; #define PG8_LDA(dst, b, h) do { _Pragma("unroll") for (int m = 0; m < 4; ++m) _Pragma("unroll") for (int k = 0; k < 2; ++k) dst[m][k] = *(const PG8_LAS bf16x8*)(lds + PG8_SA(b, h) + aoff + m * 2048 + k * 1024); } while (0)
; #define PG8_LDB(dst, b, h) do { _Pragma("unroll") for (int n = 0; n < 2; ++n) _Pragma("unroll") for (int k = 0; k < 2; ++k) dst[n][k] = *(const PG8_LAS bf16x8*)(lds + PG8_SB(b, h) + boff + n * 2048 + k * 1024); } while (0)
; #define PG8_MMA(ai, bj, At, Bt) do { __builtin_amdgcn_s_setprio(1); _Pragma("unroll") for (int m = 0; m < 4; ++m) _Pragma("unroll") for (int n = 0; n < 2; ++n) _Pragma("unroll") for (int k = 0; k < 2; ++k) \
;         acc[ai][bj][m][n] = __builtin_amdgcn_mfma_f32_16x16x32_bf16(Bt[n][k], At[m][k], acc[ai][bj][m][n], 0, 0, 0); __builtin_amdgcn_s_setprio(0); } while (0)
; #define PG8_WAIT_V(n) asm volatile("s_waitcnt vmcnt(" #n ")" ::: "memory")
; #define PG8_WAIT_L(n) asm volatile("s_waitcnt lgkmcnt(" #n ")" ::: "memory")
; #define PG8_BAR __builtin_amdgcn_s_barrier()
; #define PG8_SCHED __builtin_amdgcn_sched_barrier(0)
; template <class Epi, class Sched, bool ALIGN_EPI = false, bool SP2 = false>
; __device__ __forceinline__ void gemm_phase(PG8_LAS unsigned char* lds, const Gemm g, const Sched& S, const Epi& E) {
;     ...
;         for (int t = 0; t < nt; t += 2) {
;             const bool last = (t == nt - 2);
;             const char* a1 = cA + (size_t)(t + 1) * kstep;
;             const char* a2 = last ? nA : cA + (size_t)(t + 2) * kstep; const char* b2 = last ? nB : cB + (size_t)(t + 2) * kstep;
;             const char* a3 = a2 + kstep; const char* b3 = b2 + kstep;
;             if (last && has_next) S.a_ready(nxt);
;             if constexpr (SP2) {
;             PG8_LDB(B0, 0, 0); PG8_LDB(B1, 0, 1); PG8_SCHED; PG8_LDA(At, 0, 0); PG8_STAGE(PG8_SA(1, 1), a1 + hstep, voffA);
;             PG8_WAIT_V(8); PG8_WAIT_L(0); PG8_BAR; PG8_MMA(0, 0, At, B0); PG8_MMA(0, 1, At, B1); PG8_BAR; PG8_SCHED;
;             PG8_LDA(At, 0, 1); PG8_STAGE(PG8_SB(0, 0), b2, voffB); PG8_STAGE(PG8_SB(0, 1), b2 + hstep, voffB); PG8_STAGE(PG8_SA(0, 0), a2, voffA);
.LBB0_564:
	s_add_u32 s44, vcc_lo, 0xfffc0080
	s_addc_u32 s45, vcc_hi, -1
	s_add_i32 s85, 0, 0x10000
	s_cmp_eq_u32 s84, 12
	s_cselect_b32 s93, s36, s45
	s_cselect_b32 s92, s37, s44
	s_cselect_b32 s59, s67, s94
	s_cselect_b32 s58, s73, s88
	s_add_i32 s8, 0, 0x14000
	v_add_u32_e32 v142, s85, v201
	v_add_u32_e32 v168, s8, v201
	ds_read_b128 v[130:133], v142
	ds_read_b128 v[134:137], v142 offset:1024
	ds_read_b128 v[138:141], v142 offset:2048
	ds_read_b128 v[142:145], v142 offset:3072
	ds_read_b128 v[156:159], v168
	ds_read_b128 v[160:163], v168 offset:1024
	ds_read_b128 v[164:167], v168 offset:2048
	ds_read_b128 v[168:171], v168 offset:3072
	v_lshl_add_u64 v[208:209], vcc, 0, v[152:153]
	s_add_i32 m0, s15, 0xc000
	ds_read_b128 v[172:175], v203
	ds_read_b128 v[176:179], v203 offset:1024
	ds_read_b128 v[180:183], v203 offset:2048
	ds_read_b128 v[184:187], v203 offset:3072
	ds_read_b128 v[188:191], v203 offset:4096
	ds_read_b128 v[192:195], v203 offset:5120
	ds_read_b128 v[196:199], v203 offset:6144
	ds_read_b128 v[204:207], v203 offset:7168
	global_load_lds_dwordx4 v[208:209], off
	v_lshl_add_u64 v[208:209], vcc, 0, v[154:155]
	s_add_i32 m0, s15, 0xe000
	s_nop 0
	global_load_lds_dwordx4 v[208:209], off
	s_waitcnt vmcnt(8)
	s_waitcnt lgkmcnt(0)
	s_barrier
	s_waitcnt lgkmcnt(0)
	v_mfma_f32_16x16x32_bf16 v[124:127], v[130:133], v[172:175], v[124:127]
	v_mfma_f32_16x16x32_bf16 v[120:123], v[138:141], v[172:175], v[120:123]
	v_mfma_f32_16x16x32_bf16 v[108:111], v[130:133], v[180:183], v[108:111]
	v_mfma_f32_16x16x32_bf16 v[104:107], v[138:141], v[180:183], v[104:107]
	v_mfma_f32_16x16x32_bf16 v[92:95], v[130:133], v[188:191], v[92:95]
	v_mfma_f32_16x16x32_bf16 v[88:91], v[138:141], v[188:191], v[88:91]
	v_mfma_f32_16x16x32_bf16 v[76:79], v[130:133], v[196:199], v[76:79]
	v_mfma_f32_16x16x32_bf16 v[72:75], v[138:141], v[196:199], v[72:75]
	v_mfma_f32_16x16x32_bf16 v[124:127], v[134:137], v[176:179], v[124:127]
	v_mfma_f32_16x16x32_bf16 v[120:123], v[142:145], v[176:179], v[120:123]
	v_mfma_f32_16x16x32_bf16 v[108:111], v[134:137], v[184:187], v[108:111]
	v_mfma_f32_16x16x32_bf16 v[104:107], v[142:145], v[184:187], v[104:107]
	v_mfma_f32_16x16x32_bf16 v[92:95], v[134:137], v[192:195], v[92:95]
	v_mfma_f32_16x16x32_bf16 v[88:91], v[142:145], v[192:195], v[88:91]
	v_mfma_f32_16x16x32_bf16 v[76:79], v[134:137], v[204:207], v[76:79]
	v_mfma_f32_16x16x32_bf16 v[72:75], v[142:145], v[204:207], v[72:75]
	v_mfma_f32_16x16x32_bf16 v[116:119], v[156:159], v[172:175], v[116:119]
	v_mfma_f32_16x16x32_bf16 v[112:115], v[164:167], v[172:175], v[112:115]
	v_mfma_f32_16x16x32_bf16 v[100:103], v[156:159], v[180:183], v[100:103]
	v_mfma_f32_16x16x32_bf16 v[96:99], v[164:167], v[180:183], v[96:99]
	v_mfma_f32_16x16x32_bf16 v[84:87], v[156:159], v[188:191], v[84:87]
	v_mfma_f32_16x16x32_bf16 v[80:83], v[164:167], v[188:191], v[80:83]
	v_mfma_f32_16x16x32_bf16 v[68:71], v[156:159], v[196:199], v[68:71]
	v_mfma_f32_16x16x32_bf16 v[64:67], v[164:167], v[196:199], v[64:67]
	v_mfma_f32_16x16x32_bf16 v[116:119], v[160:163], v[176:179], v[116:119]
	v_mfma_f32_16x16x32_bf16 v[112:115], v[168:171], v[176:179], v[112:115]
	v_mfma_f32_16x16x32_bf16 v[100:103], v[160:163], v[184:187], v[100:103]
	v_mfma_f32_16x16x32_bf16 v[96:99], v[168:171], v[184:187], v[96:99]
	s_setprio 1
	v_mfma_f32_16x16x32_bf16 v[84:87], v[160:163], v[192:195], v[84:87]
	v_mfma_f32_16x16x32_bf16 v[80:83], v[168:171], v[192:195], v[80:83]
	v_mfma_f32_16x16x32_bf16 v[68:71], v[160:163], v[204:207], v[68:71]
	s_barrier
	v_mfma_f32_16x16x32_bf16 v[64:67], v[168:171], v[204:207], v[64:67]
	s_setprio 0
	s_add_i32 s44, s85, s14
	v_lshl_add_u64 v[208:209], s[58:59], 0, v[128:129]
	s_mov_b32 m0, s44
	ds_read_b128 v[172:175], v203 offset:16384
	ds_read_b128 v[176:179], v203 offset:17408
	ds_read_b128 v[180:183], v203 offset:18432
	ds_read_b128 v[184:187], v203 offset:19456
	ds_read_b128 v[188:191], v203 offset:20480
	ds_read_b128 v[192:195], v203 offset:21504
	ds_read_b128 v[196:199], v203 offset:22528
	ds_read_b128 v[204:207], v203 offset:23552
	global_load_lds_dwordx4 v[208:209], off
	s_add_i32 m0, s44, 0x2000
	s_add_u32 s44, s58, 0x40000
	v_lshl_add_u64 v[210:211], s[58:59], 0, v[146:147]
	s_addc_u32 s45, s59, 0
	s_add_i32 s8, s8, s14
	global_load_lds_dwordx4 v[210:211], off
	v_lshl_add_u64 v[214:215], s[44:45], 0, v[128:129]
	s_mov_b32 m0, s8
	v_lshl_add_u64 v[222:223], s[92:93], 0, v[148:149]
	global_load_lds_dwordx4 v[214:215], off
	v_lshl_add_u64 v[214:215], s[44:45], 0, v[146:147]
	s_add_i32 m0, s8, 0x2000
	s_nop 0
	global_load_lds_dwordx4 v[214:215], off
	v_lshl_add_u64 v[214:215], s[92:93], 0, v[150:151]
	s_mov_b32 m0, s15
	s_nop 0
	global_load_lds_dwordx4 v[214:215], off
	s_mov_b32 m0, s17
	s_nop 0
	global_load_lds_dwordx4 v[222:223], off
	s_waitcnt vmcnt(8)
	s_waitcnt lgkmcnt(0)
	s_barrier
; #define PG8_STAGE(bufoff, gbase, voff) do { _Pragma("unroll") for (int _i = 0; _i < 2; ++_i) \
;         __builtin_amdgcn_global_load_lds((const unsigned*)((const char*)(gbase) + (voff)[_i]), (PG8_LAS unsigned*)(lds + (bufoff) + ldsw + _i * 8192), 16, 0, 0); } while (0)
; #define PG8_LDA(dst, b, h) do { _Pragma("unroll") for (int m = 0; m < 4; ++m) _Pragma("unroll") for (int k = 0; k < 2; ++k) dst[m][k] = *(const PG8_LAS bf16x8*)(lds + PG8_SA(b, h) + aoff + m * 2048 + k * 1024); } while (0)
; #define PG8_LDB(dst, b, h) do { _Pragma("unroll") for (int n = 0; n < 2; ++n) _Pragma("unroll") for (int k = 0; k < 2; ++k) dst[n][k] = *(const PG8_LAS bf16x8*)(lds + PG8_SB(b, h) + boff + n * 2048 + k * 1024); } while (0)
; #define PG8_MMA(ai, bj, At, Bt) do { __builtin_amdgcn_s_setprio(1); _Pragma("unroll") for (int m = 0; m < 4; ++m) _Pragma("unroll") for (int n = 0; n < 2; ++n) _Pragma("unroll") for (int k = 0; k < 2; ++k) \
;         acc[ai][bj][m][n] = __builtin_amdgcn_mfma_f32_16x16x32_bf16(Bt[n][k], At[m][k], acc[ai][bj][m][n], 0, 0, 0); __builtin_amdgcn_s_setprio(0); } while (0)
; #define PG8_WAIT_V(n) asm volatile("s_waitcnt vmcnt(" #n ")" ::: "memory")
; #define PG8_WAIT_L(n) asm volatile("s_waitcnt lgkmcnt(" #n ")" ::: "memory")
; #define PG8_BAR __builtin_amdgcn_s_barrier()
; #define PG8_SCHED __builtin_amdgcn_sched_barrier(0)
; template <class Epi, class Sched, bool ALIGN_EPI = false, bool SP2 = false>
; __device__ __forceinline__ void gemm_phase(PG8_LAS unsigned char* lds, const Gemm g, const Sched& S, const Epi& E) {
;     ...
;             PG8_WAIT_V(8); PG8_WAIT_L(0); PG8_BAR; PG8_MMA(1, 0, At, B0); PG8_MMA(1, 1, At, B1); PG8_BAR; PG8_SCHED;
;             PG8_LDB(B0, 1, 0); PG8_LDB(B1, 1, 1); PG8_SCHED; PG8_LDA(At, 1, 0); PG8_STAGE(PG8_SA(0, 1), a2 + hstep, voffA);
;             PG8_WAIT_V(8); PG8_WAIT_L(0); PG8_BAR; PG8_MMA(0, 0, At, B0); PG8_MMA(0, 1, At, B1); PG8_BAR; PG8_SCHED;
	s_waitcnt lgkmcnt(0)
	v_mfma_f32_16x16x32_bf16 v[60:63], v[130:133], v[172:175], v[60:63]
	v_mfma_f32_16x16x32_bf16 v[56:59], v[138:141], v[172:175], v[56:59]
	v_mfma_f32_16x16x32_bf16 v[44:47], v[130:133], v[180:183], v[44:47]
	v_mfma_f32_16x16x32_bf16 v[40:43], v[138:141], v[180:183], v[40:43]
	v_mfma_f32_16x16x32_bf16 v[28:31], v[130:133], v[188:191], v[28:31]
	v_mfma_f32_16x16x32_bf16 v[24:27], v[138:141], v[188:191], v[24:27]
	v_mfma_f32_16x16x32_bf16 v[12:15], v[130:133], v[196:199], v[12:15]
	v_mfma_f32_16x16x32_bf16 v[8:11], v[138:141], v[196:199], v[8:11]
	v_mfma_f32_16x16x32_bf16 v[60:63], v[134:137], v[176:179], v[60:63]
	v_mfma_f32_16x16x32_bf16 v[56:59], v[142:145], v[176:179], v[56:59]
	v_mfma_f32_16x16x32_bf16 v[44:47], v[134:137], v[184:187], v[44:47]
	v_mfma_f32_16x16x32_bf16 v[40:43], v[142:145], v[184:187], v[40:43]
	v_mfma_f32_16x16x32_bf16 v[28:31], v[134:137], v[192:195], v[28:31]
	v_mfma_f32_16x16x32_bf16 v[24:27], v[142:145], v[192:195], v[24:27]
	v_mfma_f32_16x16x32_bf16 v[12:15], v[134:137], v[204:207], v[12:15]
	v_mfma_f32_16x16x32_bf16 v[8:11], v[142:145], v[204:207], v[8:11]
	v_mfma_f32_16x16x32_bf16 v[52:55], v[156:159], v[172:175], v[52:55]
	v_mfma_f32_16x16x32_bf16 v[48:51], v[164:167], v[172:175], v[48:51]
	v_mfma_f32_16x16x32_bf16 v[36:39], v[156:159], v[180:183], v[36:39]
	v_mfma_f32_16x16x32_bf16 v[32:35], v[164:167], v[180:183], v[32:35]
	v_mfma_f32_16x16x32_bf16 v[20:23], v[156:159], v[188:191], v[20:23]
	v_mfma_f32_16x16x32_bf16 v[16:19], v[164:167], v[188:191], v[16:19]
	v_mfma_f32_16x16x32_bf16 v[4:7], v[156:159], v[196:199], v[4:7]
	v_mfma_f32_16x16x32_bf16 v[0:3], v[164:167], v[196:199], v[0:3]
	v_mfma_f32_16x16x32_bf16 v[52:55], v[160:163], v[176:179], v[52:55]
	v_mfma_f32_16x16x32_bf16 v[48:51], v[168:171], v[176:179], v[48:51]
	v_mfma_f32_16x16x32_bf16 v[36:39], v[160:163], v[184:187], v[36:39]
	v_mfma_f32_16x16x32_bf16 v[32:35], v[168:171], v[184:187], v[32:35]
	s_setprio 1
	v_mfma_f32_16x16x32_bf16 v[20:23], v[160:163], v[192:195], v[20:23]
	v_mfma_f32_16x16x32_bf16 v[16:19], v[168:171], v[192:195], v[16:19]
	v_mfma_f32_16x16x32_bf16 v[4:7], v[160:163], v[204:207], v[4:7]
	s_barrier
	v_mfma_f32_16x16x32_bf16 v[0:3], v[168:171], v[204:207], v[0:3]
	s_setprio 0
	s_add_i32 s8, 0, 0x18000
	s_add_i32 s85, 0, 0x1c000
	v_add_u32_e32 v142, s8, v201
	v_add_u32_e32 v168, s85, v201
	ds_read_b128 v[130:133], v142
	ds_read_b128 v[134:137], v142 offset:1024
	ds_read_b128 v[138:141], v142 offset:2048
	ds_read_b128 v[142:145], v142 offset:3072
	ds_read_b128 v[156:159], v168
	ds_read_b128 v[160:163], v168 offset:1024
	ds_read_b128 v[164:167], v168 offset:2048
	ds_read_b128 v[168:171], v168 offset:3072
	s_add_u32 s44, s92, 0x40000
	s_addc_u32 s45, s93, 0
	s_mov_b32 m0, s18
	v_lshl_add_u64 v[228:229], s[44:45], 0, v[150:151]
	ds_read_b128 v[172:175], v203 offset:32768
	ds_read_b128 v[176:179], v203 offset:33792
	ds_read_b128 v[180:183], v203 offset:34816
	ds_read_b128 v[184:187], v203 offset:35840
	ds_read_b128 v[188:191], v203 offset:36864
	ds_read_b128 v[192:195], v203 offset:37888
	ds_read_b128 v[196:199], v203 offset:38912
	ds_read_b128 v[204:207], v203 offset:39936
	global_load_lds_dwordx4 v[228:229], off
	v_lshl_add_u64 v[228:229], s[44:45], 0, v[148:149]
	s_mov_b32 m0, s19
	s_nop 0
	global_load_lds_dwordx4 v[228:229], off
	s_waitcnt vmcnt(8)
	s_waitcnt lgkmcnt(0)
	s_barrier
	s_waitcnt lgkmcnt(0)
	v_mfma_f32_16x16x32_bf16 v[124:127], v[130:133], v[172:175], v[124:127]
	v_mfma_f32_16x16x32_bf16 v[120:123], v[138:141], v[172:175], v[120:123]
	v_mfma_f32_16x16x32_bf16 v[108:111], v[130:133], v[180:183], v[108:111]
	v_mfma_f32_16x16x32_bf16 v[104:107], v[138:141], v[180:183], v[104:107]
	v_mfma_f32_16x16x32_bf16 v[92:95], v[130:133], v[188:191], v[92:95]
	v_mfma_f32_16x16x32_bf16 v[88:91], v[138:141], v[188:191], v[88:91]
	v_mfma_f32_16x16x32_bf16 v[76:79], v[130:133], v[196:199], v[76:79]
	v_mfma_f32_16x16x32_bf16 v[72:75], v[138:141], v[196:199], v[72:75]
	v_mfma_f32_16x16x32_bf16 v[124:127], v[134:137], v[176:179], v[124:127]
	v_mfma_f32_16x16x32_bf16 v[120:123], v[142:145], v[176:179], v[120:123]
	v_mfma_f32_16x16x32_bf16 v[108:111], v[134:137], v[184:187], v[108:111]
	v_mfma_f32_16x16x32_bf16 v[104:107], v[142:145], v[184:187], v[104:107]
	v_mfma_f32_16x16x32_bf16 v[92:95], v[134:137], v[192:195], v[92:95]
	v_mfma_f32_16x16x32_bf16 v[88:91], v[142:145], v[192:195], v[88:91]
	v_mfma_f32_16x16x32_bf16 v[76:79], v[134:137], v[204:207], v[76:79]
	v_mfma_f32_16x16x32_bf16 v[72:75], v[142:145], v[204:207], v[72:75]
	v_mfma_f32_16x16x32_bf16 v[116:119], v[156:159], v[172:175], v[116:119]
	v_mfma_f32_16x16x32_bf16 v[112:115], v[164:167], v[172:175], v[112:115]
	v_mfma_f32_16x16x32_bf16 v[100:103], v[156:159], v[180:183], v[100:103]
	v_mfma_f32_16x16x32_bf16 v[96:99], v[164:167], v[180:183], v[96:99]
	v_mfma_f32_16x16x32_bf16 v[84:87], v[156:159], v[188:191], v[84:87]
	v_mfma_f32_16x16x32_bf16 v[80:83], v[164:167], v[188:191], v[80:83]
	v_mfma_f32_16x16x32_bf16 v[68:71], v[156:159], v[196:199], v[68:71]
	v_mfma_f32_16x16x32_bf16 v[64:67], v[164:167], v[196:199], v[64:67]
	v_mfma_f32_16x16x32_bf16 v[116:119], v[160:163], v[176:179], v[116:119]
	v_mfma_f32_16x16x32_bf16 v[112:115], v[168:171], v[176:179], v[112:115]
	v_mfma_f32_16x16x32_bf16 v[100:103], v[160:163], v[184:187], v[100:103]
	v_mfma_f32_16x16x32_bf16 v[96:99], v[168:171], v[184:187], v[96:99]
	s_setprio 1
	v_mfma_f32_16x16x32_bf16 v[84:87], v[160:163], v[192:195], v[84:87]
	v_mfma_f32_16x16x32_bf16 v[80:83], v[168:171], v[192:195], v[80:83]
	v_mfma_f32_16x16x32_bf16 v[68:71], v[160:163], v[204:207], v[68:71]
	s_barrier
; #define PG8_STAGE(bufoff, gbase, voff) do { _Pragma("unroll") for (int _i = 0; _i < 2; ++_i) \
;         __builtin_amdgcn_global_load_lds((const unsigned*)((const char*)(gbase) + (voff)[_i]), (PG8_LAS unsigned*)(lds + (bufoff) + ldsw + _i * 8192), 16, 0, 0); } while (0)
; #define PG8_LDA(dst, b, h) do { _Pragma("unroll") for (int m = 0; m < 4; ++m) _Pragma("unroll") for (int k = 0; k < 2; ++k) dst[m][k] = *(const PG8_LAS bf16x8*)(lds + PG8_SA(b, h) + aoff + m * 2048 + k * 1024); } while (0)
; #define PG8_MMA(ai, bj, At, Bt) do { __builtin_amdgcn_s_setprio(1); _Pragma("unroll") for (int m = 0; m < 4; ++m) _Pragma("unroll") for (int n = 0; n < 2; ++n) _Pragma("unroll") for (int k = 0; k < 2; ++k) \
;         acc[ai][bj][m][n] = __builtin_amdgcn_mfma_f32_16x16x32_bf16(Bt[n][k], At[m][k], acc[ai][bj][m][n], 0, 0, 0); __builtin_amdgcn_s_setprio(0); } while (0)
; #define PG8_WAIT_V(n) asm volatile("s_waitcnt vmcnt(" #n ")" ::: "memory")
; #define PG8_WAIT_L(n) asm volatile("s_waitcnt lgkmcnt(" #n ")" ::: "memory")
; #define PG8_BAR __builtin_amdgcn_s_barrier()
; #define PG8_SCHED __builtin_amdgcn_sched_barrier(0)
; template <class Epi, class Sched, bool ALIGN_EPI = false, bool SP2 = false>
; __device__ __forceinline__ void gemm_phase(PG8_LAS unsigned char* lds, const Gemm g, const Sched& S, const Epi& E) {
;     ...
;             PG8_LDA(At, 1, 1); PG8_STAGE(PG8_SB(1, 0), b3, voffB); PG8_STAGE(PG8_SB(1, 1), b3 + hstep, voffB); PG8_STAGE(PG8_SA(1, 0), a3, voffA);
;             PG8_WAIT_V(8); PG8_WAIT_L(0); PG8_BAR; PG8_MMA(1, 0, At, B0); PG8_MMA(1, 1, At, B1); PG8_BAR; PG8_SCHED;
;     ...
;         if constexpr (ALIGN_EPI) { if (wr == 0) PG8_BAR; }
	v_mfma_f32_16x16x32_bf16 v[64:67], v[168:171], v[204:207], v[64:67]
	s_setprio 0
	s_add_i32 s8, s8, s14
	v_lshl_add_u64 v[208:209], v[208:209], 0, s[90:91]
	s_mov_b32 m0, s8
	ds_read_b128 v[172:175], v203 offset:49152
	ds_read_b128 v[176:179], v203 offset:50176
	ds_read_b128 v[180:183], v203 offset:51200
	ds_read_b128 v[184:187], v203 offset:52224
	ds_read_b128 v[188:191], v203 offset:53248
	ds_read_b128 v[192:195], v203 offset:54272
	ds_read_b128 v[196:199], v203 offset:55296
	ds_read_b128 v[204:207], v203 offset:56320
	global_load_lds_dwordx4 v[208:209], off
	s_add_i32 m0, s8, 0x2000
	s_add_u32 s44, s58, 0x40080
	v_lshl_add_u64 v[208:209], v[210:211], 0, s[90:91]
	s_addc_u32 s45, s59, 0
	s_add_i32 s8, s85, s14
	global_load_lds_dwordx4 v[208:209], off
	v_lshl_add_u64 v[208:209], s[44:45], 0, v[128:129]
	s_mov_b32 m0, s8
	s_nop 0
	global_load_lds_dwordx4 v[208:209], off
	v_lshl_add_u64 v[208:209], s[44:45], 0, v[146:147]
	s_add_i32 m0, s8, 0x2000
	s_nop 0
	global_load_lds_dwordx4 v[208:209], off
	v_lshl_add_u64 v[208:209], v[214:215], 0, s[90:91]
	s_mov_b32 m0, s30
	s_nop 0
	global_load_lds_dwordx4 v[208:209], off
	v_lshl_add_u64 v[208:209], v[222:223], 0, s[90:91]
	s_mov_b32 m0, s31
	s_nop 0
	global_load_lds_dwordx4 v[208:209], off
	s_waitcnt vmcnt(8)
	s_waitcnt lgkmcnt(0)
	s_barrier
	s_waitcnt lgkmcnt(0)
	v_mfma_f32_16x16x32_bf16 v[60:63], v[130:133], v[172:175], v[60:63]
	v_mfma_f32_16x16x32_bf16 v[56:59], v[138:141], v[172:175], v[56:59]
	v_mfma_f32_16x16x32_bf16 v[44:47], v[130:133], v[180:183], v[44:47]
	v_mfma_f32_16x16x32_bf16 v[40:43], v[138:141], v[180:183], v[40:43]
	v_mfma_f32_16x16x32_bf16 v[28:31], v[130:133], v[188:191], v[28:31]
	v_mfma_f32_16x16x32_bf16 v[24:27], v[138:141], v[188:191], v[24:27]
	v_mfma_f32_16x16x32_bf16 v[12:15], v[130:133], v[196:199], v[12:15]
	v_mfma_f32_16x16x32_bf16 v[8:11], v[138:141], v[196:199], v[8:11]
	v_mfma_f32_16x16x32_bf16 v[60:63], v[134:137], v[176:179], v[60:63]
	v_mfma_f32_16x16x32_bf16 v[56:59], v[142:145], v[176:179], v[56:59]
	v_mfma_f32_16x16x32_bf16 v[44:47], v[134:137], v[184:187], v[44:47]
	v_mfma_f32_16x16x32_bf16 v[40:43], v[142:145], v[184:187], v[40:43]
	v_mfma_f32_16x16x32_bf16 v[28:31], v[134:137], v[192:195], v[28:31]
	v_mfma_f32_16x16x32_bf16 v[24:27], v[142:145], v[192:195], v[24:27]
	v_mfma_f32_16x16x32_bf16 v[12:15], v[134:137], v[204:207], v[12:15]
	v_mfma_f32_16x16x32_bf16 v[8:11], v[142:145], v[204:207], v[8:11]
	v_mfma_f32_16x16x32_bf16 v[52:55], v[156:159], v[172:175], v[52:55]
	v_mfma_f32_16x16x32_bf16 v[48:51], v[164:167], v[172:175], v[48:51]
	v_mfma_f32_16x16x32_bf16 v[36:39], v[156:159], v[180:183], v[36:39]
	v_mfma_f32_16x16x32_bf16 v[32:35], v[164:167], v[180:183], v[32:35]
	v_mfma_f32_16x16x32_bf16 v[20:23], v[156:159], v[188:191], v[20:23]
	v_mfma_f32_16x16x32_bf16 v[16:19], v[164:167], v[188:191], v[16:19]
	v_mfma_f32_16x16x32_bf16 v[4:7], v[156:159], v[196:199], v[4:7]
	v_mfma_f32_16x16x32_bf16 v[0:3], v[164:167], v[196:199], v[0:3]
	v_mfma_f32_16x16x32_bf16 v[52:55], v[160:163], v[176:179], v[52:55]
	v_mfma_f32_16x16x32_bf16 v[48:51], v[168:171], v[176:179], v[48:51]
	v_mfma_f32_16x16x32_bf16 v[36:39], v[160:163], v[184:187], v[36:39]
	v_mfma_f32_16x16x32_bf16 v[32:35], v[168:171], v[184:187], v[32:35]
	s_setprio 1
	v_mfma_f32_16x16x32_bf16 v[20:23], v[160:163], v[192:195], v[20:23]
	v_mfma_f32_16x16x32_bf16 v[16:19], v[168:171], v[192:195], v[16:19]
	v_mfma_f32_16x16x32_bf16 v[4:7], v[160:163], v[204:207], v[4:7]
	s_barrier
	v_mfma_f32_16x16x32_bf16 v[0:3], v[168:171], v[204:207], v[0:3]
	s_setprio 0
	s_add_i32 s84, s84, 2
	s_add_u32 vcc_lo, vcc_lo, 0x100
	s_addc_u32 vcc_hi, vcc_hi, 0
	s_add_u32 s88, s88, 0x100
	s_addc_u32 s94, s94, 0
	s_cmp_gt_u32 s84, 13
	s_cbranch_scc0 .LBB0_564
	s_and_b64 vcc, exec, s[62:63]
	s_cbranch_vccz .LBB0_567
	s_barrier

; #define PG8_STAGE(bufoff, gbase, voff) do { _Pragma("unroll") for (int _i = 0; _i < 2; ++_i) \
;         __builtin_amdgcn_global_load_lds((const unsigned*)((const char*)(gbase) + (voff)[_i]), (PG8_LAS unsigned*)(lds + (bufoff) + ldsw + _i * 8192), 16, 0, 0); } while (0)
; #define PG8_LDA(dst, b, h) do { _Pragma("unroll") for (int m = 0; m < 4; ++m) _Pragma("unroll") for (int k = 0; k < 2; ++k) dst[m][k] = *(const PG8_LAS bf16x8*)(lds + PG8_SA(b, h) + aoff + m * 2048 + k * 1024); } while (0)
; #define PG8_LDB(dst, b, h) do { _Pragma("unroll") for (int n = 0; n < 2; ++n) _Pragma("unroll") for (int k = 0; k < 2; ++k) dst[n][k] = *(const PG8_LAS bf16x8*)(lds + PG8_SB(b, h) + boff + n * 2048 + k * 1024); } while (0)
; #define PG8_MMA(ai, bj, At, Bt) do { __builtin_amdgcn_s_setprio(1); _Pragma("unroll") for (int m = 0; m < 4; ++m) _Pragma("unroll") for (int n = 0; n < 2; ++n) _Pragma("unroll") for (int k = 0; k < 2; ++k) \
;         acc[ai][bj][m][n] = __builtin_amdgcn_mfma_f32_16x16x32_bf16(Bt[n][k], At[m][k], acc[ai][bj][m][n], 0, 0, 0); __builtin_amdgcn_s_setprio(0); } while (0)
; #define PG8_WAIT_V(n) asm volatile("s_waitcnt vmcnt(" #n ")" ::: "memory")
; #define PG8_WAIT_L(n) asm volatile("s_waitcnt lgkmcnt(" #n ")" ::: "memory")
; #define PG8_BAR __builtin_amdgcn_s_barrier()
; #define PG8_SCHED __builtin_amdgcn_sched_barrier(0)
; template <class Epi, class Sched, bool ALIGN_EPI = false, bool SP2 = false>
; __device__ __forceinline__ void gemm_phase(PG8_LAS unsigned char* lds, const Gemm g, const Sched& S, const Epi& E) {
;     ...
;         for (int t = 0; t < nt; t += 2) {
;             const bool last = (t == nt - 2);
;             const char* a1 = cA + (size_t)(t + 1) * kstep;
;             const char* a2 = last ? nA : cA + (size_t)(t + 2) * kstep; const char* b2 = last ? nB : cB + (size_t)(t + 2) * kstep;
;             const char* a3 = a2 + kstep; const char* b3 = b2 + kstep;
;             if (last && has_next) S.a_ready(nxt);
;             if constexpr (SP2) {
;             PG8_LDB(B0, 0, 0); PG8_LDB(B1, 0, 1); PG8_SCHED; PG8_LDA(At, 0, 0); PG8_STAGE(PG8_SA(1, 1), a1 + hstep, voffA);
;             PG8_WAIT_V(8); PG8_WAIT_L(0); PG8_BAR; PG8_MMA(0, 0, At, B0); PG8_MMA(0, 1, At, B1); PG8_BAR; PG8_SCHED;
;             PG8_LDA(At, 0, 1); PG8_STAGE(PG8_SB(0, 0), b2, voffB); PG8_STAGE(PG8_SB(0, 1), b2 + hstep, voffB); PG8_STAGE(PG8_SA(0, 0), a2, voffA);
.LBB0_598:
	s_add_u32 s58, vcc_lo, 0xfffc0080
	s_addc_u32 s59, vcc_hi, -1
	s_add_i32 s84, 0, 0x10000
	s_cmp_eq_u32 s94, 12
	s_cselect_b32 s65, s35, s59
	s_cselect_b32 s64, s36, s58
	s_cselect_b32 s59, s37, s93
	s_cselect_b32 s58, s43, s88
	s_add_i32 s97, 0, 0x14000
	v_add_u32_e32 v76, s84, v228
	v_add_u32_e32 v168, s97, v228
	ds_read_b128 v[64:67], v76
	ds_read_b128 v[68:71], v76 offset:1024
	ds_read_b128 v[72:75], v76 offset:2048
	ds_read_b128 v[76:79], v76 offset:3072
	ds_read_b128 v[156:159], v168
	ds_read_b128 v[160:163], v168 offset:1024
	ds_read_b128 v[164:167], v168 offset:2048
	ds_read_b128 v[168:171], v168 offset:3072
	v_lshl_add_u64 v[204:205], vcc, 0, v[152:153]
	s_add_i32 m0, s18, 0xc000
	ds_read_b128 v[172:175], v230
	ds_read_b128 v[176:179], v230 offset:1024
	ds_read_b128 v[180:183], v230 offset:2048
	ds_read_b128 v[184:187], v230 offset:3072
	ds_read_b128 v[188:191], v230 offset:4096
	ds_read_b128 v[192:195], v230 offset:5120
	ds_read_b128 v[196:199], v230 offset:6144
	ds_read_b128 v[200:203], v230 offset:7168
	global_load_lds_dwordx4 v[204:205], off
	v_lshl_add_u64 v[204:205], vcc, 0, v[154:155]
	s_add_i32 m0, s18, 0xe000
	s_nop 0
	global_load_lds_dwordx4 v[204:205], off
	s_waitcnt vmcnt(8)
	s_waitcnt lgkmcnt(0)
	s_barrier
	s_waitcnt lgkmcnt(0)
	v_mfma_f32_16x16x32_bf16 v[142:145], v[64:67], v[172:175], v[142:145]
	v_mfma_f32_16x16x32_bf16 v[138:141], v[72:75], v[172:175], v[138:141]
	v_mfma_f32_16x16x32_bf16 v[134:137], v[64:67], v[180:183], v[134:137]
	v_mfma_f32_16x16x32_bf16 v[124:127], v[72:75], v[180:183], v[124:127]
	v_mfma_f32_16x16x32_bf16 v[108:111], v[64:67], v[188:191], v[108:111]
	v_mfma_f32_16x16x32_bf16 v[104:107], v[72:75], v[188:191], v[104:107]
	v_mfma_f32_16x16x32_bf16 v[100:103], v[64:67], v[196:199], v[100:103]
	v_mfma_f32_16x16x32_bf16 v[92:95], v[72:75], v[196:199], v[92:95]
	v_mfma_f32_16x16x32_bf16 v[142:145], v[68:71], v[176:179], v[142:145]
	v_mfma_f32_16x16x32_bf16 v[138:141], v[76:79], v[176:179], v[138:141]
	v_mfma_f32_16x16x32_bf16 v[134:137], v[68:71], v[184:187], v[134:137]
	v_mfma_f32_16x16x32_bf16 v[124:127], v[76:79], v[184:187], v[124:127]
	v_mfma_f32_16x16x32_bf16 v[108:111], v[68:71], v[192:195], v[108:111]
	v_mfma_f32_16x16x32_bf16 v[104:107], v[76:79], v[192:195], v[104:107]
	v_mfma_f32_16x16x32_bf16 v[100:103], v[68:71], v[200:203], v[100:103]
	v_mfma_f32_16x16x32_bf16 v[92:95], v[76:79], v[200:203], v[92:95]
	v_mfma_f32_16x16x32_bf16 v[130:133], v[156:159], v[172:175], v[130:133]
	v_mfma_f32_16x16x32_bf16 v[120:123], v[164:167], v[172:175], v[120:123]
	v_mfma_f32_16x16x32_bf16 v[116:119], v[156:159], v[180:183], v[116:119]
	v_mfma_f32_16x16x32_bf16 v[112:115], v[164:167], v[180:183], v[112:115]
	v_mfma_f32_16x16x32_bf16 v[96:99], v[156:159], v[188:191], v[96:99]
	v_mfma_f32_16x16x32_bf16 v[88:91], v[164:167], v[188:191], v[88:91]
	v_mfma_f32_16x16x32_bf16 v[84:87], v[156:159], v[196:199], v[84:87]
	v_mfma_f32_16x16x32_bf16 v[80:83], v[164:167], v[196:199], v[80:83]
	v_mfma_f32_16x16x32_bf16 v[130:133], v[160:163], v[176:179], v[130:133]
	v_mfma_f32_16x16x32_bf16 v[120:123], v[168:171], v[176:179], v[120:123]
	v_mfma_f32_16x16x32_bf16 v[116:119], v[160:163], v[184:187], v[116:119]
	v_mfma_f32_16x16x32_bf16 v[112:115], v[168:171], v[184:187], v[112:115]
	s_setprio 1
	v_mfma_f32_16x16x32_bf16 v[96:99], v[160:163], v[192:195], v[96:99]
	v_mfma_f32_16x16x32_bf16 v[88:91], v[168:171], v[192:195], v[88:91]
	v_mfma_f32_16x16x32_bf16 v[84:87], v[160:163], v[200:203], v[84:87]
	s_barrier
	v_mfma_f32_16x16x32_bf16 v[80:83], v[168:171], v[200:203], v[80:83]
	s_setprio 0
	s_add_i32 s84, s84, s17
	v_lshl_add_u64 v[204:205], s[58:59], 0, v[128:129]
	s_mov_b32 m0, s84
	ds_read_b128 v[172:175], v230 offset:16384
	ds_read_b128 v[176:179], v230 offset:17408
	ds_read_b128 v[180:183], v230 offset:18432
	ds_read_b128 v[184:187], v230 offset:19456
	ds_read_b128 v[188:191], v230 offset:20480
	ds_read_b128 v[192:195], v230 offset:21504
	ds_read_b128 v[196:199], v230 offset:22528
	ds_read_b128 v[200:203], v230 offset:23552
	global_load_lds_dwordx4 v[204:205], off
	s_add_i32 m0, s84, 0x2000
	s_add_u32 s84, s58, 0x40000
	v_lshl_add_u64 v[206:207], s[58:59], 0, v[146:147]
	s_addc_u32 s85, s59, 0
	s_add_i32 s97, s97, s17
	global_load_lds_dwordx4 v[206:207], off
	v_lshl_add_u64 v[208:209], s[84:85], 0, v[128:129]
	s_mov_b32 m0, s97
	v_lshl_add_u64 v[210:211], s[64:65], 0, v[148:149]
	global_load_lds_dwordx4 v[208:209], off
	v_lshl_add_u64 v[208:209], s[84:85], 0, v[146:147]
	s_add_i32 m0, s97, 0x2000
	s_nop 0
	global_load_lds_dwordx4 v[208:209], off
	v_lshl_add_u64 v[208:209], s[64:65], 0, v[150:151]
	s_mov_b32 m0, s18
	s_nop 0
	global_load_lds_dwordx4 v[208:209], off
	s_mov_b32 m0, s19
	s_nop 0
	global_load_lds_dwordx4 v[210:211], off
	s_waitcnt vmcnt(8)
	s_waitcnt lgkmcnt(0)
	s_barrier
; #define PG8_STAGE(bufoff, gbase, voff) do { _Pragma("unroll") for (int _i = 0; _i < 2; ++_i) \
;         __builtin_amdgcn_global_load_lds((const unsigned*)((const char*)(gbase) + (voff)[_i]), (PG8_LAS unsigned*)(lds + (bufoff) + ldsw + _i * 8192), 16, 0, 0); } while (0)
; #define PG8_LDA(dst, b, h) do { _Pragma("unroll") for (int m = 0; m < 4; ++m) _Pragma("unroll") for (int k = 0; k < 2; ++k) dst[m][k] = *(const PG8_LAS bf16x8*)(lds + PG8_SA(b, h) + aoff + m * 2048 + k * 1024); } while (0)
; #define PG8_LDB(dst, b, h) do { _Pragma("unroll") for (int n = 0; n < 2; ++n) _Pragma("unroll") for (int k = 0; k < 2; ++k) dst[n][k] = *(const PG8_LAS bf16x8*)(lds + PG8_SB(b, h) + boff + n * 2048 + k * 1024); } while (0)
; #define PG8_MMA(ai, bj, At, Bt) do { __builtin_amdgcn_s_setprio(1); _Pragma("unroll") for (int m = 0; m < 4; ++m) _Pragma("unroll") for (int n = 0; n < 2; ++n) _Pragma("unroll") for (int k = 0; k < 2; ++k) \
;         acc[ai][bj][m][n] = __builtin_amdgcn_mfma_f32_16x16x32_bf16(Bt[n][k], At[m][k], acc[ai][bj][m][n], 0, 0, 0); __builtin_amdgcn_s_setprio(0); } while (0)
; #define PG8_WAIT_V(n) asm volatile("s_waitcnt vmcnt(" #n ")" ::: "memory")
; #define PG8_WAIT_L(n) asm volatile("s_waitcnt lgkmcnt(" #n ")" ::: "memory")
; #define PG8_BAR __builtin_amdgcn_s_barrier()
; #define PG8_SCHED __builtin_amdgcn_sched_barrier(0)
; template <class Epi, class Sched, bool ALIGN_EPI = false, bool SP2 = false>
; __device__ __forceinline__ void gemm_phase(PG8_LAS unsigned char* lds, const Gemm g, const Sched& S, const Epi& E) {
;     ...
;             PG8_WAIT_V(8); PG8_WAIT_L(0); PG8_BAR; PG8_MMA(1, 0, At, B0); PG8_MMA(1, 1, At, B1); PG8_BAR; PG8_SCHED;
;             PG8_LDB(B0, 1, 0); PG8_LDB(B1, 1, 1); PG8_SCHED; PG8_LDA(At, 1, 0); PG8_STAGE(PG8_SA(0, 1), a2 + hstep, voffA);
;             PG8_WAIT_V(8); PG8_WAIT_L(0); PG8_BAR; PG8_MMA(0, 0, At, B0); PG8_MMA(0, 1, At, B1); PG8_BAR; PG8_SCHED;
	s_waitcnt lgkmcnt(0)
	v_mfma_f32_16x16x32_bf16 v[60:63], v[64:67], v[172:175], v[60:63]
	v_mfma_f32_16x16x32_bf16 v[56:59], v[72:75], v[172:175], v[56:59]
	v_mfma_f32_16x16x32_bf16 v[52:55], v[64:67], v[180:183], v[52:55]
	v_mfma_f32_16x16x32_bf16 v[44:47], v[72:75], v[180:183], v[44:47]
	v_mfma_f32_16x16x32_bf16 v[28:31], v[64:67], v[188:191], v[28:31]
	v_mfma_f32_16x16x32_bf16 v[24:27], v[72:75], v[188:191], v[24:27]
	v_mfma_f32_16x16x32_bf16 v[12:15], v[64:67], v[196:199], v[12:15]
	v_mfma_f32_16x16x32_bf16 v[8:11], v[72:75], v[196:199], v[8:11]
	v_mfma_f32_16x16x32_bf16 v[60:63], v[68:71], v[176:179], v[60:63]
	v_mfma_f32_16x16x32_bf16 v[56:59], v[76:79], v[176:179], v[56:59]
	v_mfma_f32_16x16x32_bf16 v[52:55], v[68:71], v[184:187], v[52:55]
	v_mfma_f32_16x16x32_bf16 v[44:47], v[76:79], v[184:187], v[44:47]
	v_mfma_f32_16x16x32_bf16 v[28:31], v[68:71], v[192:195], v[28:31]
	v_mfma_f32_16x16x32_bf16 v[24:27], v[76:79], v[192:195], v[24:27]
	v_mfma_f32_16x16x32_bf16 v[12:15], v[68:71], v[200:203], v[12:15]
	v_mfma_f32_16x16x32_bf16 v[8:11], v[76:79], v[200:203], v[8:11]
	v_mfma_f32_16x16x32_bf16 v[48:51], v[156:159], v[172:175], v[48:51]
	v_mfma_f32_16x16x32_bf16 v[40:43], v[164:167], v[172:175], v[40:43]
	v_mfma_f32_16x16x32_bf16 v[36:39], v[156:159], v[180:183], v[36:39]
	v_mfma_f32_16x16x32_bf16 v[32:35], v[164:167], v[180:183], v[32:35]
	v_mfma_f32_16x16x32_bf16 v[20:23], v[156:159], v[188:191], v[20:23]
	v_mfma_f32_16x16x32_bf16 v[16:19], v[164:167], v[188:191], v[16:19]
	v_mfma_f32_16x16x32_bf16 v[4:7], v[156:159], v[196:199], v[4:7]
	v_mfma_f32_16x16x32_bf16 v[0:3], v[164:167], v[196:199], v[0:3]
	v_mfma_f32_16x16x32_bf16 v[48:51], v[160:163], v[176:179], v[48:51]
	v_mfma_f32_16x16x32_bf16 v[40:43], v[168:171], v[176:179], v[40:43]
	v_mfma_f32_16x16x32_bf16 v[36:39], v[160:163], v[184:187], v[36:39]
	v_mfma_f32_16x16x32_bf16 v[32:35], v[168:171], v[184:187], v[32:35]
	s_setprio 1
	v_mfma_f32_16x16x32_bf16 v[20:23], v[160:163], v[192:195], v[20:23]
	v_mfma_f32_16x16x32_bf16 v[16:19], v[168:171], v[192:195], v[16:19]
	v_mfma_f32_16x16x32_bf16 v[4:7], v[160:163], v[200:203], v[4:7]
	s_barrier
	v_mfma_f32_16x16x32_bf16 v[0:3], v[168:171], v[200:203], v[0:3]
	s_setprio 0
	s_add_i32 s84, 0, 0x18000
	s_add_i32 s85, 0, 0x1c000
	v_add_u32_e32 v76, s84, v228
	v_add_u32_e32 v168, s85, v228
	ds_read_b128 v[64:67], v76
	ds_read_b128 v[68:71], v76 offset:1024
	ds_read_b128 v[72:75], v76 offset:2048
	ds_read_b128 v[76:79], v76 offset:3072
	ds_read_b128 v[156:159], v168
	ds_read_b128 v[160:163], v168 offset:1024
	ds_read_b128 v[164:167], v168 offset:2048
	ds_read_b128 v[168:171], v168 offset:3072
	s_add_u32 s64, s64, 0x40000
	s_addc_u32 s65, s65, 0
	s_mov_b32 m0, s20
	v_lshl_add_u64 v[214:215], s[64:65], 0, v[150:151]
	ds_read_b128 v[172:175], v230 offset:32768
	ds_read_b128 v[176:179], v230 offset:33792
	ds_read_b128 v[180:183], v230 offset:34816
	ds_read_b128 v[184:187], v230 offset:35840
	ds_read_b128 v[188:191], v230 offset:36864
	ds_read_b128 v[192:195], v230 offset:37888
	ds_read_b128 v[196:199], v230 offset:38912
	ds_read_b128 v[200:203], v230 offset:39936
	global_load_lds_dwordx4 v[214:215], off
	v_lshl_add_u64 v[214:215], s[64:65], 0, v[148:149]
	s_mov_b32 m0, s21
	s_nop 0
	global_load_lds_dwordx4 v[214:215], off
	s_waitcnt vmcnt(8)
	s_waitcnt lgkmcnt(0)
	s_barrier
	s_waitcnt lgkmcnt(0)
	v_mfma_f32_16x16x32_bf16 v[142:145], v[64:67], v[172:175], v[142:145]
	v_mfma_f32_16x16x32_bf16 v[138:141], v[72:75], v[172:175], v[138:141]
	v_mfma_f32_16x16x32_bf16 v[134:137], v[64:67], v[180:183], v[134:137]
	v_mfma_f32_16x16x32_bf16 v[124:127], v[72:75], v[180:183], v[124:127]
	v_mfma_f32_16x16x32_bf16 v[108:111], v[64:67], v[188:191], v[108:111]
	v_mfma_f32_16x16x32_bf16 v[104:107], v[72:75], v[188:191], v[104:107]
	v_mfma_f32_16x16x32_bf16 v[100:103], v[64:67], v[196:199], v[100:103]
	v_mfma_f32_16x16x32_bf16 v[92:95], v[72:75], v[196:199], v[92:95]
	v_mfma_f32_16x16x32_bf16 v[142:145], v[68:71], v[176:179], v[142:145]
	v_mfma_f32_16x16x32_bf16 v[138:141], v[76:79], v[176:179], v[138:141]
	v_mfma_f32_16x16x32_bf16 v[134:137], v[68:71], v[184:187], v[134:137]
	v_mfma_f32_16x16x32_bf16 v[124:127], v[76:79], v[184:187], v[124:127]
	v_mfma_f32_16x16x32_bf16 v[108:111], v[68:71], v[192:195], v[108:111]
	v_mfma_f32_16x16x32_bf16 v[104:107], v[76:79], v[192:195], v[104:107]
	v_mfma_f32_16x16x32_bf16 v[100:103], v[68:71], v[200:203], v[100:103]
	v_mfma_f32_16x16x32_bf16 v[92:95], v[76:79], v[200:203], v[92:95]
	v_mfma_f32_16x16x32_bf16 v[130:133], v[156:159], v[172:175], v[130:133]
	v_mfma_f32_16x16x32_bf16 v[120:123], v[164:167], v[172:175], v[120:123]
	v_mfma_f32_16x16x32_bf16 v[116:119], v[156:159], v[180:183], v[116:119]
	v_mfma_f32_16x16x32_bf16 v[112:115], v[164:167], v[180:183], v[112:115]
	v_mfma_f32_16x16x32_bf16 v[96:99], v[156:159], v[188:191], v[96:99]
	v_mfma_f32_16x16x32_bf16 v[88:91], v[164:167], v[188:191], v[88:91]
	v_mfma_f32_16x16x32_bf16 v[84:87], v[156:159], v[196:199], v[84:87]
	v_mfma_f32_16x16x32_bf16 v[80:83], v[164:167], v[196:199], v[80:83]
	v_mfma_f32_16x16x32_bf16 v[130:133], v[160:163], v[176:179], v[130:133]
	v_mfma_f32_16x16x32_bf16 v[120:123], v[168:171], v[176:179], v[120:123]
	v_mfma_f32_16x16x32_bf16 v[116:119], v[160:163], v[184:187], v[116:119]
	v_mfma_f32_16x16x32_bf16 v[112:115], v[168:171], v[184:187], v[112:115]
	s_setprio 1
	v_mfma_f32_16x16x32_bf16 v[96:99], v[160:163], v[192:195], v[96:99]
	v_mfma_f32_16x16x32_bf16 v[88:91], v[168:171], v[192:195], v[88:91]
	v_mfma_f32_16x16x32_bf16 v[84:87], v[160:163], v[200:203], v[84:87]
	s_barrier
; #define PG8_STAGE(bufoff, gbase, voff) do { _Pragma("unroll") for (int _i = 0; _i < 2; ++_i) \
;         __builtin_amdgcn_global_load_lds((const unsigned*)((const char*)(gbase) + (voff)[_i]), (PG8_LAS unsigned*)(lds + (bufoff) + ldsw + _i * 8192), 16, 0, 0); } while (0)
; #define PG8_LDA(dst, b, h) do { _Pragma("unroll") for (int m = 0; m < 4; ++m) _Pragma("unroll") for (int k = 0; k < 2; ++k) dst[m][k] = *(const PG8_LAS bf16x8*)(lds + PG8_SA(b, h) + aoff + m * 2048 + k * 1024); } while (0)
; #define PG8_MMA(ai, bj, At, Bt) do { __builtin_amdgcn_s_setprio(1); _Pragma("unroll") for (int m = 0; m < 4; ++m) _Pragma("unroll") for (int n = 0; n < 2; ++n) _Pragma("unroll") for (int k = 0; k < 2; ++k) \
;         acc[ai][bj][m][n] = __builtin_amdgcn_mfma_f32_16x16x32_bf16(Bt[n][k], At[m][k], acc[ai][bj][m][n], 0, 0, 0); __builtin_amdgcn_s_setprio(0); } while (0)
; #define PG8_WAIT_V(n) asm volatile("s_waitcnt vmcnt(" #n ")" ::: "memory")
; #define PG8_WAIT_L(n) asm volatile("s_waitcnt lgkmcnt(" #n ")" ::: "memory")
; #define PG8_BAR __builtin_amdgcn_s_barrier()
; #define PG8_SCHED __builtin_amdgcn_sched_barrier(0)
; template <class Epi, class Sched, bool ALIGN_EPI = false, bool SP2 = false>
; __device__ __forceinline__ void gemm_phase(PG8_LAS unsigned char* lds, const Gemm g, const Sched& S, const Epi& E) {
;     ...
;             PG8_LDA(At, 1, 1); PG8_STAGE(PG8_SB(1, 0), b3, voffB); PG8_STAGE(PG8_SB(1, 1), b3 + hstep, voffB); PG8_STAGE(PG8_SA(1, 0), a3, voffA);
;             PG8_WAIT_V(8); PG8_WAIT_L(0); PG8_BAR; PG8_MMA(1, 0, At, B0); PG8_MMA(1, 1, At, B1); PG8_BAR; PG8_SCHED;
;     ...
;         if constexpr (ALIGN_EPI) { if (wr == 0) PG8_BAR; }
	v_mfma_f32_16x16x32_bf16 v[80:83], v[168:171], v[200:203], v[80:83]
	s_setprio 0
	s_add_i32 s64, s84, s17
	v_lshl_add_u64 v[204:205], v[204:205], 0, s[90:91]
	s_mov_b32 m0, s64
	ds_read_b128 v[172:175], v230 offset:49152
	ds_read_b128 v[176:179], v230 offset:50176
	ds_read_b128 v[180:183], v230 offset:51200
	ds_read_b128 v[184:187], v230 offset:52224
	ds_read_b128 v[188:191], v230 offset:53248
	ds_read_b128 v[192:195], v230 offset:54272
	ds_read_b128 v[196:199], v230 offset:55296
	ds_read_b128 v[200:203], v230 offset:56320
	global_load_lds_dwordx4 v[204:205], off
	s_add_i32 m0, s64, 0x2000
	s_add_u32 s58, s58, 0x40080
	v_lshl_add_u64 v[204:205], v[206:207], 0, s[90:91]
	s_addc_u32 s59, s59, 0
	s_add_i32 s64, s85, s17
	global_load_lds_dwordx4 v[204:205], off
	v_lshl_add_u64 v[204:205], s[58:59], 0, v[128:129]
	s_mov_b32 m0, s64
	s_nop 0
	global_load_lds_dwordx4 v[204:205], off
	v_lshl_add_u64 v[204:205], s[58:59], 0, v[146:147]
	s_add_i32 m0, s64, 0x2000
	s_nop 0
	global_load_lds_dwordx4 v[204:205], off
	v_lshl_add_u64 v[204:205], v[208:209], 0, s[90:91]
	s_mov_b32 m0, s28
	s_nop 0
	global_load_lds_dwordx4 v[204:205], off
	v_lshl_add_u64 v[204:205], v[210:211], 0, s[90:91]
	s_mov_b32 m0, s29
	s_nop 0
	global_load_lds_dwordx4 v[204:205], off
	s_waitcnt vmcnt(8)
	s_waitcnt lgkmcnt(0)
	s_barrier
	s_waitcnt lgkmcnt(0)
	v_mfma_f32_16x16x32_bf16 v[60:63], v[64:67], v[172:175], v[60:63]
	v_mfma_f32_16x16x32_bf16 v[56:59], v[72:75], v[172:175], v[56:59]
	v_mfma_f32_16x16x32_bf16 v[52:55], v[64:67], v[180:183], v[52:55]
	v_mfma_f32_16x16x32_bf16 v[44:47], v[72:75], v[180:183], v[44:47]
	v_mfma_f32_16x16x32_bf16 v[28:31], v[64:67], v[188:191], v[28:31]
	v_mfma_f32_16x16x32_bf16 v[24:27], v[72:75], v[188:191], v[24:27]
	v_mfma_f32_16x16x32_bf16 v[12:15], v[64:67], v[196:199], v[12:15]
	v_mfma_f32_16x16x32_bf16 v[8:11], v[72:75], v[196:199], v[8:11]
	v_mfma_f32_16x16x32_bf16 v[60:63], v[68:71], v[176:179], v[60:63]
	v_mfma_f32_16x16x32_bf16 v[56:59], v[76:79], v[176:179], v[56:59]
	v_mfma_f32_16x16x32_bf16 v[52:55], v[68:71], v[184:187], v[52:55]
	v_mfma_f32_16x16x32_bf16 v[44:47], v[76:79], v[184:187], v[44:47]
	v_mfma_f32_16x16x32_bf16 v[28:31], v[68:71], v[192:195], v[28:31]
	v_mfma_f32_16x16x32_bf16 v[24:27], v[76:79], v[192:195], v[24:27]
	v_mfma_f32_16x16x32_bf16 v[12:15], v[68:71], v[200:203], v[12:15]
	v_mfma_f32_16x16x32_bf16 v[8:11], v[76:79], v[200:203], v[8:11]
	v_mfma_f32_16x16x32_bf16 v[48:51], v[156:159], v[172:175], v[48:51]
	v_mfma_f32_16x16x32_bf16 v[40:43], v[164:167], v[172:175], v[40:43]
	v_mfma_f32_16x16x32_bf16 v[36:39], v[156:159], v[180:183], v[36:39]
	v_mfma_f32_16x16x32_bf16 v[32:35], v[164:167], v[180:183], v[32:35]
	v_mfma_f32_16x16x32_bf16 v[20:23], v[156:159], v[188:191], v[20:23]
	v_mfma_f32_16x16x32_bf16 v[16:19], v[164:167], v[188:191], v[16:19]
	v_mfma_f32_16x16x32_bf16 v[4:7], v[156:159], v[196:199], v[4:7]
	v_mfma_f32_16x16x32_bf16 v[0:3], v[164:167], v[196:199], v[0:3]
	v_mfma_f32_16x16x32_bf16 v[48:51], v[160:163], v[176:179], v[48:51]
	v_mfma_f32_16x16x32_bf16 v[40:43], v[168:171], v[176:179], v[40:43]
	v_mfma_f32_16x16x32_bf16 v[36:39], v[160:163], v[184:187], v[36:39]
	v_mfma_f32_16x16x32_bf16 v[32:35], v[168:171], v[184:187], v[32:35]
	s_setprio 1
	v_mfma_f32_16x16x32_bf16 v[20:23], v[160:163], v[192:195], v[20:23]
	v_mfma_f32_16x16x32_bf16 v[16:19], v[168:171], v[192:195], v[16:19]
	v_mfma_f32_16x16x32_bf16 v[4:7], v[160:163], v[200:203], v[4:7]
	s_barrier
	v_mfma_f32_16x16x32_bf16 v[0:3], v[168:171], v[200:203], v[0:3]
	s_setprio 0
	s_add_i32 s94, s94, 2
	s_add_u32 vcc_lo, vcc_lo, 0x100
	s_addc_u32 vcc_hi, vcc_hi, 0
	s_add_u32 s88, s88, 0x100
	s_addc_u32 s93, s93, 0
	s_cmp_gt_u32 s94, 13
	s_cbranch_scc0 .LBB0_598
	s_and_b64 vcc, exec, s[72:73]
	s_cbranch_vccz .LBB0_601
	s_barrier

; #define PG8_STAGE(bufoff, gbase, voff) do { _Pragma("unroll") for (int _i = 0; _i < 2; ++_i) \
;         __builtin_amdgcn_global_load_lds((const unsigned*)((const char*)(gbase) + (voff)[_i]), (PG8_LAS unsigned*)(lds + (bufoff) + ldsw + _i * 8192), 16, 0, 0); } while (0)
; #define PG8_LDA(dst, b, h) do { _Pragma("unroll") for (int m = 0; m < 4; ++m) _Pragma("unroll") for (int k = 0; k < 2; ++k) dst[m][k] = *(const PG8_LAS bf16x8*)(lds + PG8_SA(b, h) + aoff + m * 2048 + k * 1024); } while (0)
; #define PG8_LDB(dst, b, h) do { _Pragma("unroll") for (int n = 0; n < 2; ++n) _Pragma("unroll") for (int k = 0; k < 2; ++k) dst[n][k] = *(const PG8_LAS bf16x8*)(lds + PG8_SB(b, h) + boff + n * 2048 + k * 1024); } while (0)
; #define PG8_MMA(ai, bj, At, Bt) do { __builtin_amdgcn_s_setprio(1); _Pragma("unroll") for (int m = 0; m < 4; ++m) _Pragma("unroll") for (int n = 0; n < 2; ++n) _Pragma("unroll") for (int k = 0; k < 2; ++k) \
;         acc[ai][bj][m][n] = __builtin_amdgcn_mfma_f32_16x16x32_bf16(Bt[n][k], At[m][k], acc[ai][bj][m][n], 0, 0, 0); __builtin_amdgcn_s_setprio(0); } while (0)
; #define PG8_WAIT_V(n) asm volatile("s_waitcnt vmcnt(" #n ")" ::: "memory")
; #define PG8_WAIT_L(n) asm volatile("s_waitcnt lgkmcnt(" #n ")" ::: "memory")
; #define PG8_BAR __builtin_amdgcn_s_barrier()
; #define PG8_SCHED __builtin_amdgcn_sched_barrier(0)
; template <class Epi, class Sched, bool ALIGN_EPI = false, bool SP2 = false>
; __device__ __forceinline__ void gemm_phase(PG8_LAS unsigned char* lds, const Gemm g, const Sched& S, const Epi& E) {
;     ...
;         for (int t = 0; t < nt; t += 2) {
;             const bool last = (t == nt - 2);
;             const char* a1 = cA + (size_t)(t + 1) * kstep;
;             const char* a2 = last ? nA : cA + (size_t)(t + 2) * kstep; const char* b2 = last ? nB : cB + (size_t)(t + 2) * kstep;
;             const char* a3 = a2 + kstep; const char* b3 = b2 + kstep;
;             if (last && has_next) S.a_ready(nxt);
;             if constexpr (SP2) {
;             PG8_LDB(B0, 0, 0); PG8_LDB(B1, 0, 1); PG8_SCHED; PG8_LDA(At, 0, 0); PG8_STAGE(PG8_SA(1, 1), a1 + hstep, voffA);
;             PG8_WAIT_V(8); PG8_WAIT_L(0); PG8_BAR; PG8_MMA(0, 0, At, B0); PG8_MMA(0, 1, At, B1); PG8_BAR; PG8_SCHED;
;             PG8_LDA(At, 0, 1); PG8_STAGE(PG8_SB(0, 0), b2, voffB); PG8_STAGE(PG8_SB(0, 1), b2 + hstep, voffB); PG8_STAGE(PG8_SA(0, 0), a2, voffA);
.LBB0_813:
	s_add_u32 s8, s66, 0xfffc0080
	s_addc_u32 s37, s67, -1
	s_add_i32 s49, 0, 0x10000
	s_cmp_eq_u32 s36, 12
	s_cselect_b32 s65, s28, s37
	s_cselect_b32 s64, s29, s8
	s_cselect_b32 s59, s30, s35
	s_cselect_b32 s58, s31, s34
	s_add_i32 s8, 0, 0x14000
	v_add_u32_e32 v156, s49, v145
	v_add_u32_e32 v172, s8, v145
	ds_read_b128 v[140:143], v156
	ds_read_b128 v[148:151], v156 offset:1024
	ds_read_b128 v[152:155], v156 offset:2048
	ds_read_b128 v[156:159], v156 offset:3072
	ds_read_b128 v[160:163], v172
	ds_read_b128 v[164:167], v172 offset:1024
	ds_read_b128 v[168:171], v172 offset:2048
	ds_read_b128 v[172:175], v172 offset:3072
	v_lshl_add_u64 v[208:209], s[66:67], 0, v[136:137]
	s_add_i32 m0, s18, 0xc000
	ds_read_b128 v[176:179], v147
	ds_read_b128 v[180:183], v147 offset:1024
	ds_read_b128 v[184:187], v147 offset:2048
	ds_read_b128 v[188:191], v147 offset:3072
	ds_read_b128 v[192:195], v147 offset:4096
	ds_read_b128 v[196:199], v147 offset:5120
	ds_read_b128 v[200:203], v147 offset:6144
	ds_read_b128 v[204:207], v147 offset:7168
	global_load_lds_dwordx4 v[208:209], off
	v_lshl_add_u64 v[208:209], s[66:67], 0, v[138:139]
	s_add_i32 m0, s18, 0xe000
	s_nop 0
	global_load_lds_dwordx4 v[208:209], off
	s_waitcnt vmcnt(8)
	s_waitcnt lgkmcnt(0)
	s_barrier
	s_waitcnt lgkmcnt(0)
	v_mfma_f32_16x16x32_bf16 v[124:127], v[140:143], v[176:179], v[124:127]
	v_mfma_f32_16x16x32_bf16 v[116:119], v[152:155], v[176:179], v[116:119]
	v_mfma_f32_16x16x32_bf16 v[108:111], v[140:143], v[184:187], v[108:111]
	v_mfma_f32_16x16x32_bf16 v[100:103], v[152:155], v[184:187], v[100:103]
	v_mfma_f32_16x16x32_bf16 v[92:95], v[140:143], v[192:195], v[92:95]
	v_mfma_f32_16x16x32_bf16 v[84:87], v[152:155], v[192:195], v[84:87]
	v_mfma_f32_16x16x32_bf16 v[76:79], v[140:143], v[200:203], v[76:79]
	v_mfma_f32_16x16x32_bf16 v[68:71], v[152:155], v[200:203], v[68:71]
	v_mfma_f32_16x16x32_bf16 v[124:127], v[148:151], v[180:183], v[124:127]
	v_mfma_f32_16x16x32_bf16 v[116:119], v[156:159], v[180:183], v[116:119]
	v_mfma_f32_16x16x32_bf16 v[108:111], v[148:151], v[188:191], v[108:111]
	v_mfma_f32_16x16x32_bf16 v[100:103], v[156:159], v[188:191], v[100:103]
	v_mfma_f32_16x16x32_bf16 v[92:95], v[148:151], v[196:199], v[92:95]
	v_mfma_f32_16x16x32_bf16 v[84:87], v[156:159], v[196:199], v[84:87]
	v_mfma_f32_16x16x32_bf16 v[76:79], v[148:151], v[204:207], v[76:79]
	v_mfma_f32_16x16x32_bf16 v[68:71], v[156:159], v[204:207], v[68:71]
	v_mfma_f32_16x16x32_bf16 v[120:123], v[160:163], v[176:179], v[120:123]
	v_mfma_f32_16x16x32_bf16 v[112:115], v[168:171], v[176:179], v[112:115]
	v_mfma_f32_16x16x32_bf16 v[104:107], v[160:163], v[184:187], v[104:107]
	v_mfma_f32_16x16x32_bf16 v[96:99], v[168:171], v[184:187], v[96:99]
	v_mfma_f32_16x16x32_bf16 v[88:91], v[160:163], v[192:195], v[88:91]
	v_mfma_f32_16x16x32_bf16 v[80:83], v[168:171], v[192:195], v[80:83]
	v_mfma_f32_16x16x32_bf16 v[72:75], v[160:163], v[200:203], v[72:75]
	v_mfma_f32_16x16x32_bf16 v[64:67], v[168:171], v[200:203], v[64:67]
	v_mfma_f32_16x16x32_bf16 v[120:123], v[164:167], v[180:183], v[120:123]
	v_mfma_f32_16x16x32_bf16 v[112:115], v[172:175], v[180:183], v[112:115]
	v_mfma_f32_16x16x32_bf16 v[104:107], v[164:167], v[188:191], v[104:107]
	v_mfma_f32_16x16x32_bf16 v[96:99], v[172:175], v[188:191], v[96:99]
	s_setprio 1
	v_mfma_f32_16x16x32_bf16 v[88:91], v[164:167], v[196:199], v[88:91]
	v_mfma_f32_16x16x32_bf16 v[80:83], v[172:175], v[196:199], v[80:83]
	v_mfma_f32_16x16x32_bf16 v[72:75], v[164:167], v[204:207], v[72:75]
	s_barrier
	v_mfma_f32_16x16x32_bf16 v[64:67], v[172:175], v[204:207], v[64:67]
	s_setprio 0
	s_add_i32 s37, s49, s17
	v_lshl_add_u64 v[208:209], s[58:59], 0, v[128:129]
	s_mov_b32 m0, s37
	ds_read_b128 v[176:179], v147 offset:16384
	ds_read_b128 v[180:183], v147 offset:17408
	ds_read_b128 v[184:187], v147 offset:18432
	ds_read_b128 v[188:191], v147 offset:19456
	ds_read_b128 v[192:195], v147 offset:20480
	ds_read_b128 v[196:199], v147 offset:21504
	ds_read_b128 v[200:203], v147 offset:22528
	ds_read_b128 v[204:207], v147 offset:23552
	global_load_lds_dwordx4 v[208:209], off
	s_add_i32 m0, s37, 0x2000
	s_add_u32 s72, s58, 0x40000
	v_lshl_add_u64 v[210:211], s[58:59], 0, v[130:131]
	s_addc_u32 s73, s59, 0
	s_add_i32 s8, s8, s17
	global_load_lds_dwordx4 v[210:211], off
	v_lshl_add_u64 v[214:215], s[72:73], 0, v[128:129]
	s_mov_b32 m0, s8
	v_lshl_add_u64 v[222:223], s[64:65], 0, v[132:133]
	global_load_lds_dwordx4 v[214:215], off
	v_lshl_add_u64 v[214:215], s[72:73], 0, v[130:131]
	s_add_i32 m0, s8, 0x2000
	s_nop 0
	global_load_lds_dwordx4 v[214:215], off
	v_lshl_add_u64 v[214:215], s[64:65], 0, v[134:135]
	s_mov_b32 m0, s18
	s_nop 0
	global_load_lds_dwordx4 v[214:215], off
	s_mov_b32 m0, s19
	s_nop 0
	global_load_lds_dwordx4 v[222:223], off
	s_waitcnt vmcnt(8)
	s_waitcnt lgkmcnt(0)
	s_barrier
; #define PG8_STAGE(bufoff, gbase, voff) do { _Pragma("unroll") for (int _i = 0; _i < 2; ++_i) \
;         __builtin_amdgcn_global_load_lds((const unsigned*)((const char*)(gbase) + (voff)[_i]), (PG8_LAS unsigned*)(lds + (bufoff) + ldsw + _i * 8192), 16, 0, 0); } while (0)
; #define PG8_LDA(dst, b, h) do { _Pragma("unroll") for (int m = 0; m < 4; ++m) _Pragma("unroll") for (int k = 0; k < 2; ++k) dst[m][k] = *(const PG8_LAS bf16x8*)(lds + PG8_SA(b, h) + aoff + m * 2048 + k * 1024); } while (0)
; #define PG8_LDB(dst, b, h) do { _Pragma("unroll") for (int n = 0; n < 2; ++n) _Pragma("unroll") for (int k = 0; k < 2; ++k) dst[n][k] = *(const PG8_LAS bf16x8*)(lds + PG8_SB(b, h) + boff + n * 2048 + k * 1024); } while (0)
; #define PG8_MMA(ai, bj, At, Bt) do { __builtin_amdgcn_s_setprio(1); _Pragma("unroll") for (int m = 0; m < 4; ++m) _Pragma("unroll") for (int n = 0; n < 2; ++n) _Pragma("unroll") for (int k = 0; k < 2; ++k) \
;         acc[ai][bj][m][n] = __builtin_amdgcn_mfma_f32_16x16x32_bf16(Bt[n][k], At[m][k], acc[ai][bj][m][n], 0, 0, 0); __builtin_amdgcn_s_setprio(0); } while (0)
; #define PG8_WAIT_V(n) asm volatile("s_waitcnt vmcnt(" #n ")" ::: "memory")
; #define PG8_WAIT_L(n) asm volatile("s_waitcnt lgkmcnt(" #n ")" ::: "memory")
; #define PG8_BAR __builtin_amdgcn_s_barrier()
; #define PG8_SCHED __builtin_amdgcn_sched_barrier(0)
; template <class Epi, class Sched, bool ALIGN_EPI = false, bool SP2 = false>
; __device__ __forceinline__ void gemm_phase(PG8_LAS unsigned char* lds, const Gemm g, const Sched& S, const Epi& E) {
;     ...
;             PG8_WAIT_V(8); PG8_WAIT_L(0); PG8_BAR; PG8_MMA(1, 0, At, B0); PG8_MMA(1, 1, At, B1); PG8_BAR; PG8_SCHED;
;             PG8_LDB(B0, 1, 0); PG8_LDB(B1, 1, 1); PG8_SCHED; PG8_LDA(At, 1, 0); PG8_STAGE(PG8_SA(0, 1), a2 + hstep, voffA);
;             PG8_WAIT_V(8); PG8_WAIT_L(0); PG8_BAR; PG8_MMA(0, 0, At, B0); PG8_MMA(0, 1, At, B1); PG8_BAR; PG8_SCHED;
	s_waitcnt lgkmcnt(0)
	v_mfma_f32_16x16x32_bf16 v[60:63], v[140:143], v[176:179], v[60:63]
	v_mfma_f32_16x16x32_bf16 v[52:55], v[152:155], v[176:179], v[52:55]
	v_mfma_f32_16x16x32_bf16 v[44:47], v[140:143], v[184:187], v[44:47]
	v_mfma_f32_16x16x32_bf16 v[36:39], v[152:155], v[184:187], v[36:39]
	v_mfma_f32_16x16x32_bf16 v[28:31], v[140:143], v[192:195], v[28:31]
	v_mfma_f32_16x16x32_bf16 v[20:23], v[152:155], v[192:195], v[20:23]
	v_mfma_f32_16x16x32_bf16 v[12:15], v[140:143], v[200:203], v[12:15]
	v_mfma_f32_16x16x32_bf16 v[4:7], v[152:155], v[200:203], v[4:7]
	v_mfma_f32_16x16x32_bf16 v[60:63], v[148:151], v[180:183], v[60:63]
	v_mfma_f32_16x16x32_bf16 v[52:55], v[156:159], v[180:183], v[52:55]
	v_mfma_f32_16x16x32_bf16 v[44:47], v[148:151], v[188:191], v[44:47]
	v_mfma_f32_16x16x32_bf16 v[36:39], v[156:159], v[188:191], v[36:39]
	v_mfma_f32_16x16x32_bf16 v[28:31], v[148:151], v[196:199], v[28:31]
	v_mfma_f32_16x16x32_bf16 v[20:23], v[156:159], v[196:199], v[20:23]
	v_mfma_f32_16x16x32_bf16 v[12:15], v[148:151], v[204:207], v[12:15]
	v_mfma_f32_16x16x32_bf16 v[4:7], v[156:159], v[204:207], v[4:7]
	v_mfma_f32_16x16x32_bf16 v[56:59], v[160:163], v[176:179], v[56:59]
	v_mfma_f32_16x16x32_bf16 v[48:51], v[168:171], v[176:179], v[48:51]
	v_mfma_f32_16x16x32_bf16 v[40:43], v[160:163], v[184:187], v[40:43]
	v_mfma_f32_16x16x32_bf16 v[32:35], v[168:171], v[184:187], v[32:35]
	v_mfma_f32_16x16x32_bf16 v[24:27], v[160:163], v[192:195], v[24:27]
	v_mfma_f32_16x16x32_bf16 v[16:19], v[168:171], v[192:195], v[16:19]
	v_mfma_f32_16x16x32_bf16 v[8:11], v[160:163], v[200:203], v[8:11]
	v_mfma_f32_16x16x32_bf16 v[0:3], v[168:171], v[200:203], v[0:3]
	v_mfma_f32_16x16x32_bf16 v[56:59], v[164:167], v[180:183], v[56:59]
	v_mfma_f32_16x16x32_bf16 v[48:51], v[172:175], v[180:183], v[48:51]
	v_mfma_f32_16x16x32_bf16 v[40:43], v[164:167], v[188:191], v[40:43]
	v_mfma_f32_16x16x32_bf16 v[32:35], v[172:175], v[188:191], v[32:35]
	s_setprio 1
	v_mfma_f32_16x16x32_bf16 v[24:27], v[164:167], v[196:199], v[24:27]
	v_mfma_f32_16x16x32_bf16 v[16:19], v[172:175], v[196:199], v[16:19]
	v_mfma_f32_16x16x32_bf16 v[8:11], v[164:167], v[204:207], v[8:11]
	s_barrier
	v_mfma_f32_16x16x32_bf16 v[0:3], v[172:175], v[204:207], v[0:3]
	s_setprio 0
	s_add_i32 s8, 0, 0x18000
	s_add_i32 s37, 0, 0x1c000
	v_add_u32_e32 v156, s8, v145
	v_add_u32_e32 v172, s37, v145
	ds_read_b128 v[140:143], v156
	ds_read_b128 v[148:151], v156 offset:1024
	ds_read_b128 v[152:155], v156 offset:2048
	ds_read_b128 v[156:159], v156 offset:3072
	ds_read_b128 v[160:163], v172
	ds_read_b128 v[164:167], v172 offset:1024
	ds_read_b128 v[168:171], v172 offset:2048
	ds_read_b128 v[172:175], v172 offset:3072
	s_add_u32 s64, s64, 0x40000
	s_addc_u32 s65, s65, 0
	s_mov_b32 m0, s20
	v_lshl_add_u64 v[228:229], s[64:65], 0, v[134:135]
	ds_read_b128 v[176:179], v147 offset:32768
	ds_read_b128 v[180:183], v147 offset:33792
	ds_read_b128 v[184:187], v147 offset:34816
	ds_read_b128 v[188:191], v147 offset:35840
	ds_read_b128 v[192:195], v147 offset:36864
	ds_read_b128 v[196:199], v147 offset:37888
	ds_read_b128 v[200:203], v147 offset:38912
	ds_read_b128 v[204:207], v147 offset:39936
	global_load_lds_dwordx4 v[228:229], off
	v_lshl_add_u64 v[228:229], s[64:65], 0, v[132:133]
	s_mov_b32 m0, s21
	s_nop 0
	global_load_lds_dwordx4 v[228:229], off
	s_waitcnt vmcnt(8)
	s_waitcnt lgkmcnt(0)
	s_barrier
	s_waitcnt lgkmcnt(0)
	v_mfma_f32_16x16x32_bf16 v[124:127], v[140:143], v[176:179], v[124:127]
	v_mfma_f32_16x16x32_bf16 v[116:119], v[152:155], v[176:179], v[116:119]
	v_mfma_f32_16x16x32_bf16 v[108:111], v[140:143], v[184:187], v[108:111]
	v_mfma_f32_16x16x32_bf16 v[100:103], v[152:155], v[184:187], v[100:103]
	v_mfma_f32_16x16x32_bf16 v[92:95], v[140:143], v[192:195], v[92:95]
	v_mfma_f32_16x16x32_bf16 v[84:87], v[152:155], v[192:195], v[84:87]
	v_mfma_f32_16x16x32_bf16 v[76:79], v[140:143], v[200:203], v[76:79]
	v_mfma_f32_16x16x32_bf16 v[68:71], v[152:155], v[200:203], v[68:71]
	v_mfma_f32_16x16x32_bf16 v[124:127], v[148:151], v[180:183], v[124:127]
	v_mfma_f32_16x16x32_bf16 v[116:119], v[156:159], v[180:183], v[116:119]
	v_mfma_f32_16x16x32_bf16 v[108:111], v[148:151], v[188:191], v[108:111]
	v_mfma_f32_16x16x32_bf16 v[100:103], v[156:159], v[188:191], v[100:103]
	v_mfma_f32_16x16x32_bf16 v[92:95], v[148:151], v[196:199], v[92:95]
	v_mfma_f32_16x16x32_bf16 v[84:87], v[156:159], v[196:199], v[84:87]
	v_mfma_f32_16x16x32_bf16 v[76:79], v[148:151], v[204:207], v[76:79]
	v_mfma_f32_16x16x32_bf16 v[68:71], v[156:159], v[204:207], v[68:71]
	v_mfma_f32_16x16x32_bf16 v[120:123], v[160:163], v[176:179], v[120:123]
	v_mfma_f32_16x16x32_bf16 v[112:115], v[168:171], v[176:179], v[112:115]
	v_mfma_f32_16x16x32_bf16 v[104:107], v[160:163], v[184:187], v[104:107]
	v_mfma_f32_16x16x32_bf16 v[96:99], v[168:171], v[184:187], v[96:99]
	v_mfma_f32_16x16x32_bf16 v[88:91], v[160:163], v[192:195], v[88:91]
	v_mfma_f32_16x16x32_bf16 v[80:83], v[168:171], v[192:195], v[80:83]
	v_mfma_f32_16x16x32_bf16 v[72:75], v[160:163], v[200:203], v[72:75]
	v_mfma_f32_16x16x32_bf16 v[64:67], v[168:171], v[200:203], v[64:67]
	v_mfma_f32_16x16x32_bf16 v[120:123], v[164:167], v[180:183], v[120:123]
	v_mfma_f32_16x16x32_bf16 v[112:115], v[172:175], v[180:183], v[112:115]
	v_mfma_f32_16x16x32_bf16 v[104:107], v[164:167], v[188:191], v[104:107]
	v_mfma_f32_16x16x32_bf16 v[96:99], v[172:175], v[188:191], v[96:99]
	s_setprio 1
	v_mfma_f32_16x16x32_bf16 v[88:91], v[164:167], v[196:199], v[88:91]
	v_mfma_f32_16x16x32_bf16 v[80:83], v[172:175], v[196:199], v[80:83]
	v_mfma_f32_16x16x32_bf16 v[72:75], v[164:167], v[204:207], v[72:75]
	s_barrier
; #define PG8_STAGE(bufoff, gbase, voff) do { _Pragma("unroll") for (int _i = 0; _i < 2; ++_i) \
;         __builtin_amdgcn_global_load_lds((const unsigned*)((const char*)(gbase) + (voff)[_i]), (PG8_LAS unsigned*)(lds + (bufoff) + ldsw + _i * 8192), 16, 0, 0); } while (0)
; #define PG8_LDA(dst, b, h) do { _Pragma("unroll") for (int m = 0; m < 4; ++m) _Pragma("unroll") for (int k = 0; k < 2; ++k) dst[m][k] = *(const PG8_LAS bf16x8*)(lds + PG8_SA(b, h) + aoff + m * 2048 + k * 1024); } while (0)
; #define PG8_MMA(ai, bj, At, Bt) do { __builtin_amdgcn_s_setprio(1); _Pragma("unroll") for (int m = 0; m < 4; ++m) _Pragma("unroll") for (int n = 0; n < 2; ++n) _Pragma("unroll") for (int k = 0; k < 2; ++k) \
;         acc[ai][bj][m][n] = __builtin_amdgcn_mfma_f32_16x16x32_bf16(Bt[n][k], At[m][k], acc[ai][bj][m][n], 0, 0, 0); __builtin_amdgcn_s_setprio(0); } while (0)
; #define PG8_WAIT_V(n) asm volatile("s_waitcnt vmcnt(" #n ")" ::: "memory")
; #define PG8_WAIT_L(n) asm volatile("s_waitcnt lgkmcnt(" #n ")" ::: "memory")
; #define PG8_BAR __builtin_amdgcn_s_barrier()
; #define PG8_SCHED __builtin_amdgcn_sched_barrier(0)
; template <class Epi, class Sched, bool ALIGN_EPI = false, bool SP2 = false>
; __device__ __forceinline__ void gemm_phase(PG8_LAS unsigned char* lds, const Gemm g, const Sched& S, const Epi& E) {
;     ...
;             PG8_LDA(At, 1, 1); PG8_STAGE(PG8_SB(1, 0), b3, voffB); PG8_STAGE(PG8_SB(1, 1), b3 + hstep, voffB); PG8_STAGE(PG8_SA(1, 0), a3, voffA);
;             PG8_WAIT_V(8); PG8_WAIT_L(0); PG8_BAR; PG8_MMA(1, 0, At, B0); PG8_MMA(1, 1, At, B1); PG8_BAR; PG8_SCHED;
;     ...
;         if constexpr (ALIGN_EPI) { if (wr == 0) PG8_BAR; }
	v_mfma_f32_16x16x32_bf16 v[64:67], v[172:175], v[204:207], v[64:67]
	s_setprio 0
	s_add_i32 s8, s8, s17
	v_lshl_add_u64 v[208:209], v[208:209], 0, s[90:91]
	s_mov_b32 m0, s8
	ds_read_b128 v[176:179], v147 offset:49152
	ds_read_b128 v[180:183], v147 offset:50176
	ds_read_b128 v[184:187], v147 offset:51200
	ds_read_b128 v[188:191], v147 offset:52224
	ds_read_b128 v[192:195], v147 offset:53248
	ds_read_b128 v[196:199], v147 offset:54272
	ds_read_b128 v[200:203], v147 offset:55296
	ds_read_b128 v[204:207], v147 offset:56320
	global_load_lds_dwordx4 v[208:209], off
	s_add_i32 m0, s8, 0x2000
	s_add_u32 s58, s58, 0x40080
	v_lshl_add_u64 v[208:209], v[210:211], 0, s[90:91]
	s_addc_u32 s59, s59, 0
	s_add_i32 s8, s37, s17
	global_load_lds_dwordx4 v[208:209], off
	v_lshl_add_u64 v[208:209], s[58:59], 0, v[128:129]
	s_mov_b32 m0, s8
	s_nop 0
	global_load_lds_dwordx4 v[208:209], off
	v_lshl_add_u64 v[208:209], s[58:59], 0, v[130:131]
	s_add_i32 m0, s8, 0x2000
	s_nop 0
	global_load_lds_dwordx4 v[208:209], off
	v_lshl_add_u64 v[208:209], v[214:215], 0, s[90:91]
	s_mov_b32 m0, s22
	s_nop 0
	global_load_lds_dwordx4 v[208:209], off
	v_lshl_add_u64 v[208:209], v[222:223], 0, s[90:91]
	s_mov_b32 m0, s23
	s_nop 0
	global_load_lds_dwordx4 v[208:209], off
	s_waitcnt vmcnt(8)
	s_waitcnt lgkmcnt(0)
	s_barrier
	s_waitcnt lgkmcnt(0)
	v_mfma_f32_16x16x32_bf16 v[60:63], v[140:143], v[176:179], v[60:63]
	v_mfma_f32_16x16x32_bf16 v[52:55], v[152:155], v[176:179], v[52:55]
	v_mfma_f32_16x16x32_bf16 v[44:47], v[140:143], v[184:187], v[44:47]
	v_mfma_f32_16x16x32_bf16 v[36:39], v[152:155], v[184:187], v[36:39]
	v_mfma_f32_16x16x32_bf16 v[28:31], v[140:143], v[192:195], v[28:31]
	v_mfma_f32_16x16x32_bf16 v[20:23], v[152:155], v[192:195], v[20:23]
	v_mfma_f32_16x16x32_bf16 v[12:15], v[140:143], v[200:203], v[12:15]
	v_mfma_f32_16x16x32_bf16 v[4:7], v[152:155], v[200:203], v[4:7]
	v_mfma_f32_16x16x32_bf16 v[60:63], v[148:151], v[180:183], v[60:63]
	v_mfma_f32_16x16x32_bf16 v[52:55], v[156:159], v[180:183], v[52:55]
	v_mfma_f32_16x16x32_bf16 v[44:47], v[148:151], v[188:191], v[44:47]
	v_mfma_f32_16x16x32_bf16 v[36:39], v[156:159], v[188:191], v[36:39]
	v_mfma_f32_16x16x32_bf16 v[28:31], v[148:151], v[196:199], v[28:31]
	v_mfma_f32_16x16x32_bf16 v[20:23], v[156:159], v[196:199], v[20:23]
	v_mfma_f32_16x16x32_bf16 v[12:15], v[148:151], v[204:207], v[12:15]
	v_mfma_f32_16x16x32_bf16 v[4:7], v[156:159], v[204:207], v[4:7]
	v_mfma_f32_16x16x32_bf16 v[56:59], v[160:163], v[176:179], v[56:59]
	v_mfma_f32_16x16x32_bf16 v[48:51], v[168:171], v[176:179], v[48:51]
	v_mfma_f32_16x16x32_bf16 v[40:43], v[160:163], v[184:187], v[40:43]
	v_mfma_f32_16x16x32_bf16 v[32:35], v[168:171], v[184:187], v[32:35]
	v_mfma_f32_16x16x32_bf16 v[24:27], v[160:163], v[192:195], v[24:27]
	v_mfma_f32_16x16x32_bf16 v[16:19], v[168:171], v[192:195], v[16:19]
	v_mfma_f32_16x16x32_bf16 v[8:11], v[160:163], v[200:203], v[8:11]
	v_mfma_f32_16x16x32_bf16 v[0:3], v[168:171], v[200:203], v[0:3]
	v_mfma_f32_16x16x32_bf16 v[56:59], v[164:167], v[180:183], v[56:59]
	v_mfma_f32_16x16x32_bf16 v[48:51], v[172:175], v[180:183], v[48:51]
	v_mfma_f32_16x16x32_bf16 v[40:43], v[164:167], v[188:191], v[40:43]
	v_mfma_f32_16x16x32_bf16 v[32:35], v[172:175], v[188:191], v[32:35]
	s_setprio 1
	v_mfma_f32_16x16x32_bf16 v[24:27], v[164:167], v[196:199], v[24:27]
	v_mfma_f32_16x16x32_bf16 v[16:19], v[172:175], v[196:199], v[16:19]
	v_mfma_f32_16x16x32_bf16 v[8:11], v[164:167], v[204:207], v[8:11]
	s_barrier
	v_mfma_f32_16x16x32_bf16 v[0:3], v[172:175], v[204:207], v[0:3]
	s_setprio 0
	s_add_i32 s36, s36, 2
	s_add_u32 s66, s66, 0x100
	s_addc_u32 s67, s67, 0
	s_add_u32 s34, s34, 0x100
	s_addc_u32 s35, s35, 0
	s_cmp_gt_u32 s36, 13
	s_cbranch_scc0 .LBB0_813
	s_and_b64 vcc, exec, s[46:47]
	s_cbranch_vccz .LBB0_816
	s_barrier

; #define PG8_STAGE(bufoff, gbase, voff) do { _Pragma("unroll") for (int _i = 0; _i < 2; ++_i) \
;         __builtin_amdgcn_global_load_lds((const unsigned*)((const char*)(gbase) + (voff)[_i]), (PG8_LAS unsigned*)(lds + (bufoff) + ldsw + _i * 8192), 16, 0, 0); } while (0)
; #define PG8_LDA(dst, b, h) do { _Pragma("unroll") for (int m = 0; m < 4; ++m) _Pragma("unroll") for (int k = 0; k < 2; ++k) dst[m][k] = *(const PG8_LAS bf16x8*)(lds + PG8_SA(b, h) + aoff + m * 2048 + k * 1024); } while (0)
; #define PG8_LDB(dst, b, h) do { _Pragma("unroll") for (int n = 0; n < 2; ++n) _Pragma("unroll") for (int k = 0; k < 2; ++k) dst[n][k] = *(const PG8_LAS bf16x8*)(lds + PG8_SB(b, h) + boff + n * 2048 + k * 1024); } while (0)
; #define PG8_MMA(ai, bj, At, Bt) do { __builtin_amdgcn_s_setprio(1); _Pragma("unroll") for (int m = 0; m < 4; ++m) _Pragma("unroll") for (int n = 0; n < 2; ++n) _Pragma("unroll") for (int k = 0; k < 2; ++k) \
;         acc[ai][bj][m][n] = __builtin_amdgcn_mfma_f32_16x16x32_bf16(Bt[n][k], At[m][k], acc[ai][bj][m][n], 0, 0, 0); __builtin_amdgcn_s_setprio(0); } while (0)
; #define PG8_WAIT_V(n) asm volatile("s_waitcnt vmcnt(" #n ")" ::: "memory")
; #define PG8_WAIT_L(n) asm volatile("s_waitcnt lgkmcnt(" #n ")" ::: "memory")
; #define PG8_BAR __builtin_amdgcn_s_barrier()
; #define PG8_SCHED __builtin_amdgcn_sched_barrier(0)
; template <class Epi, class Sched, bool ALIGN_EPI = false, bool SP2 = false>
; __device__ __forceinline__ void gemm_phase(PG8_LAS unsigned char* lds, const Gemm g, const Sched& S, const Epi& E) {
;     ...
;         for (int t = 0; t < nt; t += 2) {
;             const bool last = (t == nt - 2);
;             const char* a1 = cA + (size_t)(t + 1) * kstep;
;             const char* a2 = last ? nA : cA + (size_t)(t + 2) * kstep; const char* b2 = last ? nB : cB + (size_t)(t + 2) * kstep;
;             const char* a3 = a2 + kstep; const char* b3 = b2 + kstep;
;             if (last && has_next) S.a_ready(nxt);
;             if constexpr (SP2) {
;             PG8_LDB(B0, 0, 0); PG8_LDB(B1, 0, 1); PG8_SCHED; PG8_LDA(At, 0, 0); PG8_STAGE(PG8_SA(1, 1), a1 + hstep, voffA);
;             PG8_WAIT_V(8); PG8_WAIT_L(0); PG8_BAR; PG8_MMA(0, 0, At, B0); PG8_MMA(0, 1, At, B1); PG8_BAR; PG8_SCHED;
;             PG8_LDA(At, 0, 1); PG8_STAGE(PG8_SB(0, 0), b2, voffB); PG8_STAGE(PG8_SB(0, 1), b2 + hstep, voffB); PG8_STAGE(PG8_SA(0, 0), a2, voffA);
.LBB0_957:
	s_add_u32 s44, s96, 0x100
	s_addc_u32 s45, s97, 0
	s_add_i32 s8, 0, 0x10000
	s_cmp_eq_u32 s70, 40
	s_cselect_b32 s65, s67, s45
	s_cselect_b32 s64, s66, s44
	s_cselect_b32 s47, s73, s37
	s_cselect_b32 s46, s72, s36
	s_add_i32 s88, 0, 0x14000
	v_add_u32_e32 v142, s8, v185
	v_add_u32_e32 v168, s88, v185
	ds_read_b128 v[130:133], v142
	ds_read_b128 v[134:137], v142 offset:1024
	ds_read_b128 v[138:141], v142 offset:2048
	ds_read_b128 v[142:145], v142 offset:3072
	ds_read_b128 v[156:159], v168
	ds_read_b128 v[160:163], v168 offset:1024
	ds_read_b128 v[164:167], v168 offset:2048
	ds_read_b128 v[168:171], v168 offset:3072
	v_lshl_add_u64 v[208:209], s[96:97], 0, v[152:153]
	s_add_i32 m0, s15, 0xc000
	ds_read_b128 v[172:175], v191
	ds_read_b128 v[176:179], v191 offset:1024
	ds_read_b128 v[180:183], v191 offset:2048
	ds_read_b128 v[186:189], v191 offset:3072
	ds_read_b128 v[192:195], v191 offset:4096
	ds_read_b128 v[196:199], v191 offset:5120
	ds_read_b128 v[200:203], v191 offset:6144
	ds_read_b128 v[204:207], v191 offset:7168
	global_load_lds_dwordx4 v[208:209], off
	v_lshl_add_u64 v[208:209], s[96:97], 0, v[154:155]
	s_add_i32 m0, s15, 0xe000
	s_nop 0
	global_load_lds_dwordx4 v[208:209], off
	s_waitcnt vmcnt(8)
	s_waitcnt lgkmcnt(0)
	s_barrier
	s_waitcnt lgkmcnt(0)
	v_mfma_f32_16x16x32_bf16 v[124:127], v[130:133], v[172:175], v[124:127]
	v_mfma_f32_16x16x32_bf16 v[120:123], v[138:141], v[172:175], v[120:123]
	v_mfma_f32_16x16x32_bf16 v[108:111], v[130:133], v[180:183], v[108:111]
	v_mfma_f32_16x16x32_bf16 v[104:107], v[138:141], v[180:183], v[104:107]
	v_mfma_f32_16x16x32_bf16 v[92:95], v[130:133], v[192:195], v[92:95]
	v_mfma_f32_16x16x32_bf16 v[88:91], v[138:141], v[192:195], v[88:91]
	v_mfma_f32_16x16x32_bf16 v[76:79], v[130:133], v[200:203], v[76:79]
	v_mfma_f32_16x16x32_bf16 v[72:75], v[138:141], v[200:203], v[72:75]
	v_mfma_f32_16x16x32_bf16 v[124:127], v[134:137], v[176:179], v[124:127]
	v_mfma_f32_16x16x32_bf16 v[120:123], v[142:145], v[176:179], v[120:123]
	v_mfma_f32_16x16x32_bf16 v[108:111], v[134:137], v[186:189], v[108:111]
	v_mfma_f32_16x16x32_bf16 v[104:107], v[142:145], v[186:189], v[104:107]
	v_mfma_f32_16x16x32_bf16 v[92:95], v[134:137], v[196:199], v[92:95]
	v_mfma_f32_16x16x32_bf16 v[88:91], v[142:145], v[196:199], v[88:91]
	v_mfma_f32_16x16x32_bf16 v[76:79], v[134:137], v[204:207], v[76:79]
	v_mfma_f32_16x16x32_bf16 v[72:75], v[142:145], v[204:207], v[72:75]
	v_mfma_f32_16x16x32_bf16 v[116:119], v[156:159], v[172:175], v[116:119]
	v_mfma_f32_16x16x32_bf16 v[112:115], v[164:167], v[172:175], v[112:115]
	v_mfma_f32_16x16x32_bf16 v[100:103], v[156:159], v[180:183], v[100:103]
	v_mfma_f32_16x16x32_bf16 v[96:99], v[164:167], v[180:183], v[96:99]
	v_mfma_f32_16x16x32_bf16 v[84:87], v[156:159], v[192:195], v[84:87]
	v_mfma_f32_16x16x32_bf16 v[80:83], v[164:167], v[192:195], v[80:83]
	v_mfma_f32_16x16x32_bf16 v[68:71], v[156:159], v[200:203], v[68:71]
	v_mfma_f32_16x16x32_bf16 v[64:67], v[164:167], v[200:203], v[64:67]
	v_mfma_f32_16x16x32_bf16 v[116:119], v[160:163], v[176:179], v[116:119]
	v_mfma_f32_16x16x32_bf16 v[112:115], v[168:171], v[176:179], v[112:115]
	v_mfma_f32_16x16x32_bf16 v[100:103], v[160:163], v[186:189], v[100:103]
	v_mfma_f32_16x16x32_bf16 v[96:99], v[168:171], v[186:189], v[96:99]
	s_setprio 1
	v_mfma_f32_16x16x32_bf16 v[84:87], v[160:163], v[196:199], v[84:87]
	v_mfma_f32_16x16x32_bf16 v[80:83], v[168:171], v[196:199], v[80:83]
	v_mfma_f32_16x16x32_bf16 v[68:71], v[160:163], v[204:207], v[68:71]
	s_barrier
	v_mfma_f32_16x16x32_bf16 v[64:67], v[168:171], v[204:207], v[64:67]
	s_setprio 0
	s_add_i32 s8, s8, s14
	v_lshl_add_u64 v[208:209], s[46:47], 0, v[128:129]
	s_mov_b32 m0, s8
	ds_read_b128 v[172:175], v191 offset:16384
	ds_read_b128 v[176:179], v191 offset:17408
	ds_read_b128 v[180:183], v191 offset:18432
	ds_read_b128 v[186:189], v191 offset:19456
	ds_read_b128 v[192:195], v191 offset:20480
	ds_read_b128 v[196:199], v191 offset:21504
	ds_read_b128 v[200:203], v191 offset:22528
	ds_read_b128 v[204:207], v191 offset:23552
	global_load_lds_dwordx4 v[208:209], off
	s_add_i32 m0, s8, 0x2000
	s_add_u32 s84, s46, 0xb0000
	v_lshl_add_u64 v[210:211], s[46:47], 0, v[146:147]
	s_addc_u32 s85, s47, 0
	s_add_i32 s8, s88, s14
	global_load_lds_dwordx4 v[210:211], off
	v_lshl_add_u64 v[214:215], s[84:85], 0, v[128:129]
	s_mov_b32 m0, s8
	v_lshl_add_u64 v[222:223], s[64:65], 0, v[148:149]
	global_load_lds_dwordx4 v[214:215], off
	v_lshl_add_u64 v[214:215], s[84:85], 0, v[146:147]
	s_add_i32 m0, s8, 0x2000
	s_nop 0
	global_load_lds_dwordx4 v[214:215], off
	v_lshl_add_u64 v[214:215], s[64:65], 0, v[150:151]
	s_mov_b32 m0, s15
	s_nop 0
	global_load_lds_dwordx4 v[214:215], off
	s_mov_b32 m0, s18
	s_nop 0
	global_load_lds_dwordx4 v[222:223], off
	s_waitcnt vmcnt(8)
	s_waitcnt lgkmcnt(0)
	s_barrier
; #define PG8_STAGE(bufoff, gbase, voff) do { _Pragma("unroll") for (int _i = 0; _i < 2; ++_i) \
;         __builtin_amdgcn_global_load_lds((const unsigned*)((const char*)(gbase) + (voff)[_i]), (PG8_LAS unsigned*)(lds + (bufoff) + ldsw + _i * 8192), 16, 0, 0); } while (0)
; #define PG8_LDA(dst, b, h) do { _Pragma("unroll") for (int m = 0; m < 4; ++m) _Pragma("unroll") for (int k = 0; k < 2; ++k) dst[m][k] = *(const PG8_LAS bf16x8*)(lds + PG8_SA(b, h) + aoff + m * 2048 + k * 1024); } while (0)
; #define PG8_LDB(dst, b, h) do { _Pragma("unroll") for (int n = 0; n < 2; ++n) _Pragma("unroll") for (int k = 0; k < 2; ++k) dst[n][k] = *(const PG8_LAS bf16x8*)(lds + PG8_SB(b, h) + boff + n * 2048 + k * 1024); } while (0)
; #define PG8_MMA(ai, bj, At, Bt) do { __builtin_amdgcn_s_setprio(1); _Pragma("unroll") for (int m = 0; m < 4; ++m) _Pragma("unroll") for (int n = 0; n < 2; ++n) _Pragma("unroll") for (int k = 0; k < 2; ++k) \
;         acc[ai][bj][m][n] = __builtin_amdgcn_mfma_f32_16x16x32_bf16(Bt[n][k], At[m][k], acc[ai][bj][m][n], 0, 0, 0); __builtin_amdgcn_s_setprio(0); } while (0)
; #define PG8_WAIT_V(n) asm volatile("s_waitcnt vmcnt(" #n ")" ::: "memory")
; #define PG8_WAIT_L(n) asm volatile("s_waitcnt lgkmcnt(" #n ")" ::: "memory")
; #define PG8_BAR __builtin_amdgcn_s_barrier()
; #define PG8_SCHED __builtin_amdgcn_sched_barrier(0)
; template <class Epi, class Sched, bool ALIGN_EPI = false, bool SP2 = false>
; __device__ __forceinline__ void gemm_phase(PG8_LAS unsigned char* lds, const Gemm g, const Sched& S, const Epi& E) {
;     ...
;             PG8_WAIT_V(8); PG8_WAIT_L(0); PG8_BAR; PG8_MMA(1, 0, At, B0); PG8_MMA(1, 1, At, B1); PG8_BAR; PG8_SCHED;
;             PG8_LDB(B0, 1, 0); PG8_LDB(B1, 1, 1); PG8_SCHED; PG8_LDA(At, 1, 0); PG8_STAGE(PG8_SA(0, 1), a2 + hstep, voffA);
;             PG8_WAIT_V(8); PG8_WAIT_L(0); PG8_BAR; PG8_MMA(0, 0, At, B0); PG8_MMA(0, 1, At, B1); PG8_BAR; PG8_SCHED;
	s_waitcnt lgkmcnt(0)
	v_mfma_f32_16x16x32_bf16 v[60:63], v[130:133], v[172:175], v[60:63]
	v_mfma_f32_16x16x32_bf16 v[56:59], v[138:141], v[172:175], v[56:59]
	v_mfma_f32_16x16x32_bf16 v[44:47], v[130:133], v[180:183], v[44:47]
	v_mfma_f32_16x16x32_bf16 v[40:43], v[138:141], v[180:183], v[40:43]
	v_mfma_f32_16x16x32_bf16 v[28:31], v[130:133], v[192:195], v[28:31]
	v_mfma_f32_16x16x32_bf16 v[24:27], v[138:141], v[192:195], v[24:27]
	v_mfma_f32_16x16x32_bf16 v[12:15], v[130:133], v[200:203], v[12:15]
	v_mfma_f32_16x16x32_bf16 v[8:11], v[138:141], v[200:203], v[8:11]
	v_mfma_f32_16x16x32_bf16 v[60:63], v[134:137], v[176:179], v[60:63]
	v_mfma_f32_16x16x32_bf16 v[56:59], v[142:145], v[176:179], v[56:59]
	v_mfma_f32_16x16x32_bf16 v[44:47], v[134:137], v[186:189], v[44:47]
	v_mfma_f32_16x16x32_bf16 v[40:43], v[142:145], v[186:189], v[40:43]
	v_mfma_f32_16x16x32_bf16 v[28:31], v[134:137], v[196:199], v[28:31]
	v_mfma_f32_16x16x32_bf16 v[24:27], v[142:145], v[196:199], v[24:27]
	v_mfma_f32_16x16x32_bf16 v[12:15], v[134:137], v[204:207], v[12:15]
	v_mfma_f32_16x16x32_bf16 v[8:11], v[142:145], v[204:207], v[8:11]
	v_mfma_f32_16x16x32_bf16 v[52:55], v[156:159], v[172:175], v[52:55]
	v_mfma_f32_16x16x32_bf16 v[48:51], v[164:167], v[172:175], v[48:51]
	v_mfma_f32_16x16x32_bf16 v[36:39], v[156:159], v[180:183], v[36:39]
	v_mfma_f32_16x16x32_bf16 v[32:35], v[164:167], v[180:183], v[32:35]
	v_mfma_f32_16x16x32_bf16 v[20:23], v[156:159], v[192:195], v[20:23]
	v_mfma_f32_16x16x32_bf16 v[16:19], v[164:167], v[192:195], v[16:19]
	v_mfma_f32_16x16x32_bf16 v[4:7], v[156:159], v[200:203], v[4:7]
	v_mfma_f32_16x16x32_bf16 v[0:3], v[164:167], v[200:203], v[0:3]
	v_mfma_f32_16x16x32_bf16 v[52:55], v[160:163], v[176:179], v[52:55]
	v_mfma_f32_16x16x32_bf16 v[48:51], v[168:171], v[176:179], v[48:51]
	v_mfma_f32_16x16x32_bf16 v[36:39], v[160:163], v[186:189], v[36:39]
	v_mfma_f32_16x16x32_bf16 v[32:35], v[168:171], v[186:189], v[32:35]
	s_setprio 1
	v_mfma_f32_16x16x32_bf16 v[20:23], v[160:163], v[196:199], v[20:23]
	v_mfma_f32_16x16x32_bf16 v[16:19], v[168:171], v[196:199], v[16:19]
	v_mfma_f32_16x16x32_bf16 v[4:7], v[160:163], v[204:207], v[4:7]
	s_barrier
	v_mfma_f32_16x16x32_bf16 v[0:3], v[168:171], v[204:207], v[0:3]
	s_setprio 0
	s_add_i32 s8, 0, 0x18000
	s_add_i32 s84, 0, 0x1c000
	v_add_u32_e32 v142, s8, v185
	v_add_u32_e32 v168, s84, v185
	ds_read_b128 v[130:133], v142
	ds_read_b128 v[134:137], v142 offset:1024
	ds_read_b128 v[138:141], v142 offset:2048
	ds_read_b128 v[142:145], v142 offset:3072
	ds_read_b128 v[156:159], v168
	ds_read_b128 v[160:163], v168 offset:1024
	ds_read_b128 v[164:167], v168 offset:2048
	ds_read_b128 v[168:171], v168 offset:3072
	s_add_u32 s64, s64, 0xb0000
	s_addc_u32 s65, s65, 0
	s_mov_b32 m0, s19
	v_lshl_add_u64 v[228:229], s[64:65], 0, v[150:151]
	ds_read_b128 v[172:175], v191 offset:32768
	ds_read_b128 v[176:179], v191 offset:33792
	ds_read_b128 v[180:183], v191 offset:34816
	ds_read_b128 v[186:189], v191 offset:35840
	ds_read_b128 v[192:195], v191 offset:36864
	ds_read_b128 v[196:199], v191 offset:37888
	ds_read_b128 v[200:203], v191 offset:38912
	ds_read_b128 v[204:207], v191 offset:39936
	global_load_lds_dwordx4 v[228:229], off
	v_lshl_add_u64 v[228:229], s[64:65], 0, v[148:149]
	s_mov_b32 m0, s20
	s_nop 0
	global_load_lds_dwordx4 v[228:229], off
	s_waitcnt vmcnt(8)
	s_waitcnt lgkmcnt(0)
	s_barrier
	s_waitcnt lgkmcnt(0)
	v_mfma_f32_16x16x32_bf16 v[124:127], v[130:133], v[172:175], v[124:127]
	v_mfma_f32_16x16x32_bf16 v[120:123], v[138:141], v[172:175], v[120:123]
	v_mfma_f32_16x16x32_bf16 v[108:111], v[130:133], v[180:183], v[108:111]
	v_mfma_f32_16x16x32_bf16 v[104:107], v[138:141], v[180:183], v[104:107]
	v_mfma_f32_16x16x32_bf16 v[92:95], v[130:133], v[192:195], v[92:95]
	v_mfma_f32_16x16x32_bf16 v[88:91], v[138:141], v[192:195], v[88:91]
	v_mfma_f32_16x16x32_bf16 v[76:79], v[130:133], v[200:203], v[76:79]
	v_mfma_f32_16x16x32_bf16 v[72:75], v[138:141], v[200:203], v[72:75]
	v_mfma_f32_16x16x32_bf16 v[124:127], v[134:137], v[176:179], v[124:127]
	v_mfma_f32_16x16x32_bf16 v[120:123], v[142:145], v[176:179], v[120:123]
	v_mfma_f32_16x16x32_bf16 v[108:111], v[134:137], v[186:189], v[108:111]
	v_mfma_f32_16x16x32_bf16 v[104:107], v[142:145], v[186:189], v[104:107]
	v_mfma_f32_16x16x32_bf16 v[92:95], v[134:137], v[196:199], v[92:95]
	v_mfma_f32_16x16x32_bf16 v[88:91], v[142:145], v[196:199], v[88:91]
	v_mfma_f32_16x16x32_bf16 v[76:79], v[134:137], v[204:207], v[76:79]
	v_mfma_f32_16x16x32_bf16 v[72:75], v[142:145], v[204:207], v[72:75]
	v_mfma_f32_16x16x32_bf16 v[116:119], v[156:159], v[172:175], v[116:119]
	v_mfma_f32_16x16x32_bf16 v[112:115], v[164:167], v[172:175], v[112:115]
	v_mfma_f32_16x16x32_bf16 v[100:103], v[156:159], v[180:183], v[100:103]
	v_mfma_f32_16x16x32_bf16 v[96:99], v[164:167], v[180:183], v[96:99]
	v_mfma_f32_16x16x32_bf16 v[84:87], v[156:159], v[192:195], v[84:87]
	v_mfma_f32_16x16x32_bf16 v[80:83], v[164:167], v[192:195], v[80:83]
	v_mfma_f32_16x16x32_bf16 v[68:71], v[156:159], v[200:203], v[68:71]
	v_mfma_f32_16x16x32_bf16 v[64:67], v[164:167], v[200:203], v[64:67]
	v_mfma_f32_16x16x32_bf16 v[116:119], v[160:163], v[176:179], v[116:119]
	v_mfma_f32_16x16x32_bf16 v[112:115], v[168:171], v[176:179], v[112:115]
	v_mfma_f32_16x16x32_bf16 v[100:103], v[160:163], v[186:189], v[100:103]
	v_mfma_f32_16x16x32_bf16 v[96:99], v[168:171], v[186:189], v[96:99]
	s_setprio 1
	v_mfma_f32_16x16x32_bf16 v[84:87], v[160:163], v[196:199], v[84:87]
	v_mfma_f32_16x16x32_bf16 v[80:83], v[168:171], v[196:199], v[80:83]
	v_mfma_f32_16x16x32_bf16 v[68:71], v[160:163], v[204:207], v[68:71]
	s_barrier
; #define PG8_STAGE(bufoff, gbase, voff) do { _Pragma("unroll") for (int _i = 0; _i < 2; ++_i) \
;         __builtin_amdgcn_global_load_lds((const unsigned*)((const char*)(gbase) + (voff)[_i]), (PG8_LAS unsigned*)(lds + (bufoff) + ldsw + _i * 8192), 16, 0, 0); } while (0)
; #define PG8_LDA(dst, b, h) do { _Pragma("unroll") for (int m = 0; m < 4; ++m) _Pragma("unroll") for (int k = 0; k < 2; ++k) dst[m][k] = *(const PG8_LAS bf16x8*)(lds + PG8_SA(b, h) + aoff + m * 2048 + k * 1024); } while (0)
; #define PG8_MMA(ai, bj, At, Bt) do { __builtin_amdgcn_s_setprio(1); _Pragma("unroll") for (int m = 0; m < 4; ++m) _Pragma("unroll") for (int n = 0; n < 2; ++n) _Pragma("unroll") for (int k = 0; k < 2; ++k) \
;         acc[ai][bj][m][n] = __builtin_amdgcn_mfma_f32_16x16x32_bf16(Bt[n][k], At[m][k], acc[ai][bj][m][n], 0, 0, 0); __builtin_amdgcn_s_setprio(0); } while (0)
; #define PG8_WAIT_V(n) asm volatile("s_waitcnt vmcnt(" #n ")" ::: "memory")
; #define PG8_WAIT_L(n) asm volatile("s_waitcnt lgkmcnt(" #n ")" ::: "memory")
; #define PG8_BAR __builtin_amdgcn_s_barrier()
; #define PG8_SCHED __builtin_amdgcn_sched_barrier(0)
; template <class Epi, class Sched, bool ALIGN_EPI = false, bool SP2 = false>
; __device__ __forceinline__ void gemm_phase(PG8_LAS unsigned char* lds, const Gemm g, const Sched& S, const Epi& E) {
;     ...
;             PG8_LDA(At, 1, 1); PG8_STAGE(PG8_SB(1, 0), b3, voffB); PG8_STAGE(PG8_SB(1, 1), b3 + hstep, voffB); PG8_STAGE(PG8_SA(1, 0), a3, voffA);
;             PG8_WAIT_V(8); PG8_WAIT_L(0); PG8_BAR; PG8_MMA(1, 0, At, B0); PG8_MMA(1, 1, At, B1); PG8_BAR; PG8_SCHED;
;     ...
;         if constexpr (ALIGN_EPI) { if (wr == 0) PG8_BAR; }
	v_mfma_f32_16x16x32_bf16 v[64:67], v[168:171], v[204:207], v[64:67]
	s_setprio 0
	s_add_i32 s8, s8, s14
	v_lshl_add_u64 v[208:209], v[208:209], 0, s[90:91]
	s_mov_b32 m0, s8
	ds_read_b128 v[172:175], v191 offset:49152
	ds_read_b128 v[176:179], v191 offset:50176
	ds_read_b128 v[180:183], v191 offset:51200
	ds_read_b128 v[186:189], v191 offset:52224
	ds_read_b128 v[192:195], v191 offset:53248
	ds_read_b128 v[196:199], v191 offset:54272
	ds_read_b128 v[200:203], v191 offset:55296
	ds_read_b128 v[204:207], v191 offset:56320
	global_load_lds_dwordx4 v[208:209], off
	s_add_i32 m0, s8, 0x2000
	s_add_u32 s46, s46, 0xb0080
	v_lshl_add_u64 v[208:209], v[210:211], 0, s[90:91]
	s_addc_u32 s47, s47, 0
	s_add_i32 s8, s84, s14
	global_load_lds_dwordx4 v[208:209], off
	v_lshl_add_u64 v[208:209], s[46:47], 0, v[128:129]
	s_mov_b32 m0, s8
	s_nop 0
	global_load_lds_dwordx4 v[208:209], off
	v_lshl_add_u64 v[208:209], s[46:47], 0, v[146:147]
	s_add_i32 m0, s8, 0x2000
	s_nop 0
	global_load_lds_dwordx4 v[208:209], off
	v_lshl_add_u64 v[208:209], v[214:215], 0, s[90:91]
	s_mov_b32 m0, s27
	s_nop 0
	global_load_lds_dwordx4 v[208:209], off
	v_lshl_add_u64 v[208:209], v[222:223], 0, s[90:91]
	s_mov_b32 m0, s28
	s_nop 0
	global_load_lds_dwordx4 v[208:209], off
	s_waitcnt vmcnt(8)
	s_waitcnt lgkmcnt(0)
	s_barrier
	s_waitcnt lgkmcnt(0)
	v_mfma_f32_16x16x32_bf16 v[60:63], v[130:133], v[172:175], v[60:63]
	v_mfma_f32_16x16x32_bf16 v[56:59], v[138:141], v[172:175], v[56:59]
	v_mfma_f32_16x16x32_bf16 v[44:47], v[130:133], v[180:183], v[44:47]
	v_mfma_f32_16x16x32_bf16 v[40:43], v[138:141], v[180:183], v[40:43]
	v_mfma_f32_16x16x32_bf16 v[28:31], v[130:133], v[192:195], v[28:31]
	v_mfma_f32_16x16x32_bf16 v[24:27], v[138:141], v[192:195], v[24:27]
	v_mfma_f32_16x16x32_bf16 v[12:15], v[130:133], v[200:203], v[12:15]
	v_mfma_f32_16x16x32_bf16 v[8:11], v[138:141], v[200:203], v[8:11]
	v_mfma_f32_16x16x32_bf16 v[60:63], v[134:137], v[176:179], v[60:63]
	v_mfma_f32_16x16x32_bf16 v[56:59], v[142:145], v[176:179], v[56:59]
	v_mfma_f32_16x16x32_bf16 v[44:47], v[134:137], v[186:189], v[44:47]
	v_mfma_f32_16x16x32_bf16 v[40:43], v[142:145], v[186:189], v[40:43]
	v_mfma_f32_16x16x32_bf16 v[28:31], v[134:137], v[196:199], v[28:31]
	v_mfma_f32_16x16x32_bf16 v[24:27], v[142:145], v[196:199], v[24:27]
	v_mfma_f32_16x16x32_bf16 v[12:15], v[134:137], v[204:207], v[12:15]
	v_mfma_f32_16x16x32_bf16 v[8:11], v[142:145], v[204:207], v[8:11]
	v_mfma_f32_16x16x32_bf16 v[52:55], v[156:159], v[172:175], v[52:55]
	v_mfma_f32_16x16x32_bf16 v[48:51], v[164:167], v[172:175], v[48:51]
	v_mfma_f32_16x16x32_bf16 v[36:39], v[156:159], v[180:183], v[36:39]
	v_mfma_f32_16x16x32_bf16 v[32:35], v[164:167], v[180:183], v[32:35]
	v_mfma_f32_16x16x32_bf16 v[20:23], v[156:159], v[192:195], v[20:23]
	v_mfma_f32_16x16x32_bf16 v[16:19], v[164:167], v[192:195], v[16:19]
	v_mfma_f32_16x16x32_bf16 v[4:7], v[156:159], v[200:203], v[4:7]
	v_mfma_f32_16x16x32_bf16 v[0:3], v[164:167], v[200:203], v[0:3]
	v_mfma_f32_16x16x32_bf16 v[52:55], v[160:163], v[176:179], v[52:55]
	v_mfma_f32_16x16x32_bf16 v[48:51], v[168:171], v[176:179], v[48:51]
	v_mfma_f32_16x16x32_bf16 v[36:39], v[160:163], v[186:189], v[36:39]
	v_mfma_f32_16x16x32_bf16 v[32:35], v[168:171], v[186:189], v[32:35]
	s_setprio 1
	v_mfma_f32_16x16x32_bf16 v[20:23], v[160:163], v[196:199], v[20:23]
	v_mfma_f32_16x16x32_bf16 v[16:19], v[168:171], v[196:199], v[16:19]
	v_mfma_f32_16x16x32_bf16 v[4:7], v[160:163], v[204:207], v[4:7]
	s_barrier
	v_mfma_f32_16x16x32_bf16 v[0:3], v[168:171], v[204:207], v[0:3]
	s_setprio 0
	s_add_i32 s70, s70, 2
	s_add_u32 s36, s36, 0x100
	s_addc_u32 s37, s37, 0
	s_cmp_gt_u32 s70, 41
	s_mov_b64 s[96:97], s[44:45]
	s_cbranch_scc0 .LBB0_957
	s_and_b64 vcc, exec, s[58:59]
	s_cbranch_vccz .LBB0_960
	s_barrier

; #define PG8_STAGE(bufoff, gbase, voff) do { _Pragma("unroll") for (int _i = 0; _i < 2; ++_i) \
;         __builtin_amdgcn_global_load_lds((const unsigned*)((const char*)(gbase) + (voff)[_i]), (PG8_LAS unsigned*)(lds + (bufoff) + ldsw + _i * 8192), 16, 0, 0); } while (0)
; #define PG8_LDA(dst, b, h) do { _Pragma("unroll") for (int m = 0; m < 4; ++m) _Pragma("unroll") for (int k = 0; k < 2; ++k) dst[m][k] = *(const PG8_LAS bf16x8*)(lds + PG8_SA(b, h) + aoff + m * 2048 + k * 1024); } while (0)
; #define PG8_LDB(dst, b, h) do { _Pragma("unroll") for (int n = 0; n < 2; ++n) _Pragma("unroll") for (int k = 0; k < 2; ++k) dst[n][k] = *(const PG8_LAS bf16x8*)(lds + PG8_SB(b, h) + boff + n * 2048 + k * 1024); } while (0)
; #define PG8_MMA(ai, bj, At, Bt) do { __builtin_amdgcn_s_setprio(1); _Pragma("unroll") for (int m = 0; m < 4; ++m) _Pragma("unroll") for (int n = 0; n < 2; ++n) _Pragma("unroll") for (int k = 0; k < 2; ++k) \
;         acc[ai][bj][m][n] = __builtin_amdgcn_mfma_f32_16x16x32_bf16(Bt[n][k], At[m][k], acc[ai][bj][m][n], 0, 0, 0); __builtin_amdgcn_s_setprio(0); } while (0)
; #define PG8_WAIT_V(n) asm volatile("s_waitcnt vmcnt(" #n ")" ::: "memory")
; #define PG8_WAIT_L(n) asm volatile("s_waitcnt lgkmcnt(" #n ")" ::: "memory")
; template <class Epi, class Sched, bool ALIGN_EPI = false, bool SP2 = false>
; __device__ __forceinline__ void gemm_phase(PG8_LAS unsigned char* lds, const Gemm g, const Sched& S, const Epi& E) {
;     ...
;             const bool last = (t == nt - 2);
;             const char* a1 = cA + (size_t)(t + 1) * kstep;
;             const char* a2 = last ? nA : cA + (size_t)(t + 2) * kstep; const char* b2 = last ? nB : cB + (size_t)(t + 2) * kstep;
;             const char* a3 = a2 + kstep; const char* b3 = b2 + kstep;
;             if (last && has_next) S.a_ready(nxt);
;             if constexpr (SP2) {
;             PG8_LDB(B0, 0, 0); PG8_LDB(B1, 0, 1); PG8_SCHED; PG8_LDA(At, 0, 0); PG8_STAGE(PG8_SA(1, 1), a1 + hstep, voffA);
;             PG8_WAIT_V(8); PG8_WAIT_L(0); PG8_BAR; PG8_MMA(0, 0, At, B0); PG8_MMA(0, 1, At, B1); PG8_BAR; PG8_SCHED;
;             PG8_LDA(At, 0, 1); PG8_STAGE(PG8_SB(0, 0), b2, voffB); PG8_STAGE(PG8_SB(0, 1), b2 + hstep, voffB); PG8_STAGE(PG8_SA(0, 0), a2, voffA);
;             PG8_WAIT_V(8); PG8_WAIT_L(0); PG8_BAR; PG8_MMA(1, 0, At, B0); PG8_MMA(1, 1, At, B1); PG8_BAR; PG8_SCHED;
.LBB0_995:
	s_add_u32 s42, s96, 0x100
	s_addc_u32 s43, s97, 0
	s_add_i32 s8, 0, 0x10000
	s_cmp_eq_u32 s84, 40
	s_cselect_b32 s65, s67, s43
	s_cselect_b32 s64, s66, s42
	s_cselect_b32 s47, s73, s37
	s_cselect_b32 s46, s72, s36
	s_add_i32 s85, 0, 0x14000
	v_add_u32_e32 v142, s8, v201
	v_add_u32_e32 v168, s85, v201
	ds_read_b128 v[130:133], v142
	ds_read_b128 v[134:137], v142 offset:1024
	ds_read_b128 v[138:141], v142 offset:2048
	ds_read_b128 v[142:145], v142 offset:3072
	ds_read_b128 v[156:159], v168
	ds_read_b128 v[160:163], v168 offset:1024
	ds_read_b128 v[164:167], v168 offset:2048
	ds_read_b128 v[168:171], v168 offset:3072
	v_lshl_add_u64 v[208:209], s[96:97], 0, v[152:153]
	s_add_i32 m0, s15, 0xc000
	ds_read_b128 v[172:175], v203
	ds_read_b128 v[176:179], v203 offset:1024
	ds_read_b128 v[180:183], v203 offset:2048
	ds_read_b128 v[184:187], v203 offset:3072
	ds_read_b128 v[188:191], v203 offset:4096
	ds_read_b128 v[192:195], v203 offset:5120
	ds_read_b128 v[196:199], v203 offset:6144
	ds_read_b128 v[204:207], v203 offset:7168
	global_load_lds_dwordx4 v[208:209], off
	v_lshl_add_u64 v[208:209], s[96:97], 0, v[154:155]
	s_add_i32 m0, s15, 0xe000
	s_nop 0
	global_load_lds_dwordx4 v[208:209], off
	s_waitcnt vmcnt(8)
	s_waitcnt lgkmcnt(0)
	s_barrier
	s_waitcnt lgkmcnt(0)
	v_mfma_f32_16x16x32_bf16 v[124:127], v[130:133], v[172:175], v[124:127]
	v_mfma_f32_16x16x32_bf16 v[120:123], v[138:141], v[172:175], v[120:123]
	v_mfma_f32_16x16x32_bf16 v[108:111], v[130:133], v[180:183], v[108:111]
	v_mfma_f32_16x16x32_bf16 v[104:107], v[138:141], v[180:183], v[104:107]
	v_mfma_f32_16x16x32_bf16 v[92:95], v[130:133], v[188:191], v[92:95]
	v_mfma_f32_16x16x32_bf16 v[88:91], v[138:141], v[188:191], v[88:91]
	v_mfma_f32_16x16x32_bf16 v[76:79], v[130:133], v[196:199], v[76:79]
	v_mfma_f32_16x16x32_bf16 v[72:75], v[138:141], v[196:199], v[72:75]
	v_mfma_f32_16x16x32_bf16 v[124:127], v[134:137], v[176:179], v[124:127]
	v_mfma_f32_16x16x32_bf16 v[120:123], v[142:145], v[176:179], v[120:123]
	v_mfma_f32_16x16x32_bf16 v[108:111], v[134:137], v[184:187], v[108:111]
	v_mfma_f32_16x16x32_bf16 v[104:107], v[142:145], v[184:187], v[104:107]
	v_mfma_f32_16x16x32_bf16 v[92:95], v[134:137], v[192:195], v[92:95]
	v_mfma_f32_16x16x32_bf16 v[88:91], v[142:145], v[192:195], v[88:91]
	v_mfma_f32_16x16x32_bf16 v[76:79], v[134:137], v[204:207], v[76:79]
	v_mfma_f32_16x16x32_bf16 v[72:75], v[142:145], v[204:207], v[72:75]
	v_mfma_f32_16x16x32_bf16 v[116:119], v[156:159], v[172:175], v[116:119]
	v_mfma_f32_16x16x32_bf16 v[112:115], v[164:167], v[172:175], v[112:115]
	v_mfma_f32_16x16x32_bf16 v[100:103], v[156:159], v[180:183], v[100:103]
	v_mfma_f32_16x16x32_bf16 v[96:99], v[164:167], v[180:183], v[96:99]
	v_mfma_f32_16x16x32_bf16 v[84:87], v[156:159], v[188:191], v[84:87]
	v_mfma_f32_16x16x32_bf16 v[80:83], v[164:167], v[188:191], v[80:83]
	v_mfma_f32_16x16x32_bf16 v[68:71], v[156:159], v[196:199], v[68:71]
	v_mfma_f32_16x16x32_bf16 v[64:67], v[164:167], v[196:199], v[64:67]
	v_mfma_f32_16x16x32_bf16 v[116:119], v[160:163], v[176:179], v[116:119]
	v_mfma_f32_16x16x32_bf16 v[112:115], v[168:171], v[176:179], v[112:115]
	v_mfma_f32_16x16x32_bf16 v[100:103], v[160:163], v[184:187], v[100:103]
	v_mfma_f32_16x16x32_bf16 v[96:99], v[168:171], v[184:187], v[96:99]
	s_setprio 1
	v_mfma_f32_16x16x32_bf16 v[84:87], v[160:163], v[192:195], v[84:87]
	v_mfma_f32_16x16x32_bf16 v[80:83], v[168:171], v[192:195], v[80:83]
	v_mfma_f32_16x16x32_bf16 v[68:71], v[160:163], v[204:207], v[68:71]
	s_barrier
	v_mfma_f32_16x16x32_bf16 v[64:67], v[168:171], v[204:207], v[64:67]
	s_setprio 0
	s_add_i32 s8, s8, s14
	v_lshl_add_u64 v[208:209], s[46:47], 0, v[128:129]
	s_mov_b32 m0, s8
	ds_read_b128 v[172:175], v203 offset:16384
	ds_read_b128 v[176:179], v203 offset:17408
	ds_read_b128 v[180:183], v203 offset:18432
	ds_read_b128 v[184:187], v203 offset:19456
	ds_read_b128 v[188:191], v203 offset:20480
	ds_read_b128 v[192:195], v203 offset:21504
	ds_read_b128 v[196:199], v203 offset:22528
	ds_read_b128 v[204:207], v203 offset:23552
	global_load_lds_dwordx4 v[208:209], off
	s_add_i32 m0, s8, 0x2000
	s_add_u32 s96, s46, 0xb0000
	v_lshl_add_u64 v[210:211], s[46:47], 0, v[146:147]
	s_addc_u32 s97, s47, 0
	s_add_i32 s8, s85, s14
	global_load_lds_dwordx4 v[210:211], off
	v_lshl_add_u64 v[214:215], s[96:97], 0, v[128:129]
	s_mov_b32 m0, s8
	v_lshl_add_u64 v[222:223], s[64:65], 0, v[148:149]
	global_load_lds_dwordx4 v[214:215], off
	v_lshl_add_u64 v[214:215], s[96:97], 0, v[146:147]
	s_add_i32 m0, s8, 0x2000
	s_nop 0
	global_load_lds_dwordx4 v[214:215], off
	v_lshl_add_u64 v[214:215], s[64:65], 0, v[150:151]
	s_mov_b32 m0, s15
	s_nop 0
	global_load_lds_dwordx4 v[214:215], off
	s_mov_b32 m0, s18
	s_nop 0
	global_load_lds_dwordx4 v[222:223], off
	s_waitcnt vmcnt(8)
	s_waitcnt lgkmcnt(0)
	s_barrier
; #define PG8_STAGE(bufoff, gbase, voff) do { _Pragma("unroll") for (int _i = 0; _i < 2; ++_i) \
;         __builtin_amdgcn_global_load_lds((const unsigned*)((const char*)(gbase) + (voff)[_i]), (PG8_LAS unsigned*)(lds + (bufoff) + ldsw + _i * 8192), 16, 0, 0); } while (0)
; #define PG8_LDA(dst, b, h) do { _Pragma("unroll") for (int m = 0; m < 4; ++m) _Pragma("unroll") for (int k = 0; k < 2; ++k) dst[m][k] = *(const PG8_LAS bf16x8*)(lds + PG8_SA(b, h) + aoff + m * 2048 + k * 1024); } while (0)
; #define PG8_LDB(dst, b, h) do { _Pragma("unroll") for (int n = 0; n < 2; ++n) _Pragma("unroll") for (int k = 0; k < 2; ++k) dst[n][k] = *(const PG8_LAS bf16x8*)(lds + PG8_SB(b, h) + boff + n * 2048 + k * 1024); } while (0)
; #define PG8_MMA(ai, bj, At, Bt) do { __builtin_amdgcn_s_setprio(1); _Pragma("unroll") for (int m = 0; m < 4; ++m) _Pragma("unroll") for (int n = 0; n < 2; ++n) _Pragma("unroll") for (int k = 0; k < 2; ++k) \
;         acc[ai][bj][m][n] = __builtin_amdgcn_mfma_f32_16x16x32_bf16(Bt[n][k], At[m][k], acc[ai][bj][m][n], 0, 0, 0); __builtin_amdgcn_s_setprio(0); } while (0)
; #define PG8_WAIT_V(n) asm volatile("s_waitcnt vmcnt(" #n ")" ::: "memory")
; #define PG8_WAIT_L(n) asm volatile("s_waitcnt lgkmcnt(" #n ")" ::: "memory")
; #define PG8_BAR __builtin_amdgcn_s_barrier()
; #define PG8_SCHED __builtin_amdgcn_sched_barrier(0)
; template <class Epi, class Sched, bool ALIGN_EPI = false, bool SP2 = false>
; __device__ __forceinline__ void gemm_phase(PG8_LAS unsigned char* lds, const Gemm g, const Sched& S, const Epi& E) {
;     ...
;             PG8_WAIT_V(8); PG8_WAIT_L(0); PG8_BAR; PG8_MMA(1, 0, At, B0); PG8_MMA(1, 1, At, B1); PG8_BAR; PG8_SCHED;
;             PG8_LDB(B0, 1, 0); PG8_LDB(B1, 1, 1); PG8_SCHED; PG8_LDA(At, 1, 0); PG8_STAGE(PG8_SA(0, 1), a2 + hstep, voffA);
;             PG8_WAIT_V(8); PG8_WAIT_L(0); PG8_BAR; PG8_MMA(0, 0, At, B0); PG8_MMA(0, 1, At, B1); PG8_BAR; PG8_SCHED;
	s_waitcnt lgkmcnt(0)
	v_mfma_f32_16x16x32_bf16 v[60:63], v[130:133], v[172:175], v[60:63]
	v_mfma_f32_16x16x32_bf16 v[56:59], v[138:141], v[172:175], v[56:59]
	v_mfma_f32_16x16x32_bf16 v[44:47], v[130:133], v[180:183], v[44:47]
	v_mfma_f32_16x16x32_bf16 v[40:43], v[138:141], v[180:183], v[40:43]
	v_mfma_f32_16x16x32_bf16 v[28:31], v[130:133], v[188:191], v[28:31]
	v_mfma_f32_16x16x32_bf16 v[24:27], v[138:141], v[188:191], v[24:27]
	v_mfma_f32_16x16x32_bf16 v[12:15], v[130:133], v[196:199], v[12:15]
	v_mfma_f32_16x16x32_bf16 v[8:11], v[138:141], v[196:199], v[8:11]
	v_mfma_f32_16x16x32_bf16 v[60:63], v[134:137], v[176:179], v[60:63]
	v_mfma_f32_16x16x32_bf16 v[56:59], v[142:145], v[176:179], v[56:59]
	v_mfma_f32_16x16x32_bf16 v[44:47], v[134:137], v[184:187], v[44:47]
	v_mfma_f32_16x16x32_bf16 v[40:43], v[142:145], v[184:187], v[40:43]
	v_mfma_f32_16x16x32_bf16 v[28:31], v[134:137], v[192:195], v[28:31]
	v_mfma_f32_16x16x32_bf16 v[24:27], v[142:145], v[192:195], v[24:27]
	v_mfma_f32_16x16x32_bf16 v[12:15], v[134:137], v[204:207], v[12:15]
	v_mfma_f32_16x16x32_bf16 v[8:11], v[142:145], v[204:207], v[8:11]
	v_mfma_f32_16x16x32_bf16 v[52:55], v[156:159], v[172:175], v[52:55]
	v_mfma_f32_16x16x32_bf16 v[48:51], v[164:167], v[172:175], v[48:51]
	v_mfma_f32_16x16x32_bf16 v[36:39], v[156:159], v[180:183], v[36:39]
	v_mfma_f32_16x16x32_bf16 v[32:35], v[164:167], v[180:183], v[32:35]
	v_mfma_f32_16x16x32_bf16 v[20:23], v[156:159], v[188:191], v[20:23]
	v_mfma_f32_16x16x32_bf16 v[16:19], v[164:167], v[188:191], v[16:19]
	v_mfma_f32_16x16x32_bf16 v[4:7], v[156:159], v[196:199], v[4:7]
	v_mfma_f32_16x16x32_bf16 v[0:3], v[164:167], v[196:199], v[0:3]
	v_mfma_f32_16x16x32_bf16 v[52:55], v[160:163], v[176:179], v[52:55]
	v_mfma_f32_16x16x32_bf16 v[48:51], v[168:171], v[176:179], v[48:51]
	v_mfma_f32_16x16x32_bf16 v[36:39], v[160:163], v[184:187], v[36:39]
	v_mfma_f32_16x16x32_bf16 v[32:35], v[168:171], v[184:187], v[32:35]
	s_setprio 1
	v_mfma_f32_16x16x32_bf16 v[20:23], v[160:163], v[192:195], v[20:23]
	v_mfma_f32_16x16x32_bf16 v[16:19], v[168:171], v[192:195], v[16:19]
	v_mfma_f32_16x16x32_bf16 v[4:7], v[160:163], v[204:207], v[4:7]
	s_barrier
	v_mfma_f32_16x16x32_bf16 v[0:3], v[168:171], v[204:207], v[0:3]
	s_setprio 0
	s_add_i32 s8, 0, 0x18000
	s_add_i32 s85, 0, 0x1c000
	v_add_u32_e32 v142, s8, v201
	v_add_u32_e32 v168, s85, v201
	ds_read_b128 v[130:133], v142
	ds_read_b128 v[134:137], v142 offset:1024
	ds_read_b128 v[138:141], v142 offset:2048
	ds_read_b128 v[142:145], v142 offset:3072
	ds_read_b128 v[156:159], v168
	ds_read_b128 v[160:163], v168 offset:1024
	ds_read_b128 v[164:167], v168 offset:2048
	ds_read_b128 v[168:171], v168 offset:3072
	s_add_u32 s64, s64, 0xb0000
	s_addc_u32 s65, s65, 0
	s_mov_b32 m0, s19
	v_lshl_add_u64 v[228:229], s[64:65], 0, v[150:151]
	ds_read_b128 v[172:175], v203 offset:32768
	ds_read_b128 v[176:179], v203 offset:33792
	ds_read_b128 v[180:183], v203 offset:34816
	ds_read_b128 v[184:187], v203 offset:35840
	ds_read_b128 v[188:191], v203 offset:36864
	ds_read_b128 v[192:195], v203 offset:37888
	ds_read_b128 v[196:199], v203 offset:38912
	ds_read_b128 v[204:207], v203 offset:39936
	global_load_lds_dwordx4 v[228:229], off
	v_lshl_add_u64 v[228:229], s[64:65], 0, v[148:149]
	s_mov_b32 m0, s20
	s_nop 0
	global_load_lds_dwordx4 v[228:229], off
	s_waitcnt vmcnt(8)
	s_waitcnt lgkmcnt(0)
	s_barrier
	s_waitcnt lgkmcnt(0)
	v_mfma_f32_16x16x32_bf16 v[124:127], v[130:133], v[172:175], v[124:127]
	v_mfma_f32_16x16x32_bf16 v[120:123], v[138:141], v[172:175], v[120:123]
	v_mfma_f32_16x16x32_bf16 v[108:111], v[130:133], v[180:183], v[108:111]
	v_mfma_f32_16x16x32_bf16 v[104:107], v[138:141], v[180:183], v[104:107]
	v_mfma_f32_16x16x32_bf16 v[92:95], v[130:133], v[188:191], v[92:95]
	v_mfma_f32_16x16x32_bf16 v[88:91], v[138:141], v[188:191], v[88:91]
	v_mfma_f32_16x16x32_bf16 v[76:79], v[130:133], v[196:199], v[76:79]
	v_mfma_f32_16x16x32_bf16 v[72:75], v[138:141], v[196:199], v[72:75]
	v_mfma_f32_16x16x32_bf16 v[124:127], v[134:137], v[176:179], v[124:127]
	v_mfma_f32_16x16x32_bf16 v[120:123], v[142:145], v[176:179], v[120:123]
	v_mfma_f32_16x16x32_bf16 v[108:111], v[134:137], v[184:187], v[108:111]
	v_mfma_f32_16x16x32_bf16 v[104:107], v[142:145], v[184:187], v[104:107]
	v_mfma_f32_16x16x32_bf16 v[92:95], v[134:137], v[192:195], v[92:95]
	v_mfma_f32_16x16x32_bf16 v[88:91], v[142:145], v[192:195], v[88:91]
	v_mfma_f32_16x16x32_bf16 v[76:79], v[134:137], v[204:207], v[76:79]
	v_mfma_f32_16x16x32_bf16 v[72:75], v[142:145], v[204:207], v[72:75]
	v_mfma_f32_16x16x32_bf16 v[116:119], v[156:159], v[172:175], v[116:119]
	v_mfma_f32_16x16x32_bf16 v[112:115], v[164:167], v[172:175], v[112:115]
	v_mfma_f32_16x16x32_bf16 v[100:103], v[156:159], v[180:183], v[100:103]
	v_mfma_f32_16x16x32_bf16 v[96:99], v[164:167], v[180:183], v[96:99]
	v_mfma_f32_16x16x32_bf16 v[84:87], v[156:159], v[188:191], v[84:87]
	v_mfma_f32_16x16x32_bf16 v[80:83], v[164:167], v[188:191], v[80:83]
	v_mfma_f32_16x16x32_bf16 v[68:71], v[156:159], v[196:199], v[68:71]
	v_mfma_f32_16x16x32_bf16 v[64:67], v[164:167], v[196:199], v[64:67]
	v_mfma_f32_16x16x32_bf16 v[116:119], v[160:163], v[176:179], v[116:119]
	v_mfma_f32_16x16x32_bf16 v[112:115], v[168:171], v[176:179], v[112:115]
	v_mfma_f32_16x16x32_bf16 v[100:103], v[160:163], v[184:187], v[100:103]
	v_mfma_f32_16x16x32_bf16 v[96:99], v[168:171], v[184:187], v[96:99]
	s_setprio 1
	v_mfma_f32_16x16x32_bf16 v[84:87], v[160:163], v[192:195], v[84:87]
	v_mfma_f32_16x16x32_bf16 v[80:83], v[168:171], v[192:195], v[80:83]
	v_mfma_f32_16x16x32_bf16 v[68:71], v[160:163], v[204:207], v[68:71]
	s_barrier
; #define PG8_STAGE(bufoff, gbase, voff) do { _Pragma("unroll") for (int _i = 0; _i < 2; ++_i) \
;         __builtin_amdgcn_global_load_lds((const unsigned*)((const char*)(gbase) + (voff)[_i]), (PG8_LAS unsigned*)(lds + (bufoff) + ldsw + _i * 8192), 16, 0, 0); } while (0)
; #define PG8_LDA(dst, b, h) do { _Pragma("unroll") for (int m = 0; m < 4; ++m) _Pragma("unroll") for (int k = 0; k < 2; ++k) dst[m][k] = *(const PG8_LAS bf16x8*)(lds + PG8_SA(b, h) + aoff + m * 2048 + k * 1024); } while (0)
; #define PG8_MMA(ai, bj, At, Bt) do { __builtin_amdgcn_s_setprio(1); _Pragma("unroll") for (int m = 0; m < 4; ++m) _Pragma("unroll") for (int n = 0; n < 2; ++n) _Pragma("unroll") for (int k = 0; k < 2; ++k) \
;         acc[ai][bj][m][n] = __builtin_amdgcn_mfma_f32_16x16x32_bf16(Bt[n][k], At[m][k], acc[ai][bj][m][n], 0, 0, 0); __builtin_amdgcn_s_setprio(0); } while (0)
; #define PG8_WAIT_V(n) asm volatile("s_waitcnt vmcnt(" #n ")" ::: "memory")
; #define PG8_WAIT_L(n) asm volatile("s_waitcnt lgkmcnt(" #n ")" ::: "memory")
; #define PG8_BAR __builtin_amdgcn_s_barrier()
; #define PG8_SCHED __builtin_amdgcn_sched_barrier(0)
; template <class Epi, class Sched, bool ALIGN_EPI = false, bool SP2 = false>
; __device__ __forceinline__ void gemm_phase(PG8_LAS unsigned char* lds, const Gemm g, const Sched& S, const Epi& E) {
;     ...
;             PG8_WAIT_V(8); PG8_WAIT_L(0); PG8_BAR; PG8_MMA(0, 0, At, B0); PG8_MMA(0, 1, At, B1); PG8_BAR; PG8_SCHED;
;             PG8_LDA(At, 1, 1); PG8_STAGE(PG8_SB(1, 0), b3, voffB); PG8_STAGE(PG8_SB(1, 1), b3 + hstep, voffB); PG8_STAGE(PG8_SA(1, 0), a3, voffA);
;             PG8_WAIT_V(8); PG8_WAIT_L(0); PG8_BAR; PG8_MMA(1, 0, At, B0); PG8_MMA(1, 1, At, B1); PG8_BAR; PG8_SCHED;
;     ...
;         if constexpr (ALIGN_EPI) { if (wr == 0) PG8_BAR; }
	v_mfma_f32_16x16x32_bf16 v[64:67], v[168:171], v[204:207], v[64:67]
	s_setprio 0
	s_add_i32 s8, s8, s14
	v_lshl_add_u64 v[208:209], v[208:209], 0, s[90:91]
	s_mov_b32 m0, s8
	ds_read_b128 v[172:175], v203 offset:49152
	ds_read_b128 v[176:179], v203 offset:50176
	ds_read_b128 v[180:183], v203 offset:51200
	ds_read_b128 v[184:187], v203 offset:52224
	ds_read_b128 v[188:191], v203 offset:53248
	ds_read_b128 v[192:195], v203 offset:54272
	ds_read_b128 v[196:199], v203 offset:55296
	ds_read_b128 v[204:207], v203 offset:56320
	global_load_lds_dwordx4 v[208:209], off
	s_add_i32 m0, s8, 0x2000
	s_add_u32 s46, s46, 0xb0080
	v_lshl_add_u64 v[208:209], v[210:211], 0, s[90:91]
	s_addc_u32 s47, s47, 0
	s_add_i32 s8, s85, s14
	global_load_lds_dwordx4 v[208:209], off
	v_lshl_add_u64 v[208:209], s[46:47], 0, v[128:129]
	s_mov_b32 m0, s8
	s_nop 0
	global_load_lds_dwordx4 v[208:209], off
	v_lshl_add_u64 v[208:209], s[46:47], 0, v[146:147]
	s_add_i32 m0, s8, 0x2000
	s_nop 0
	global_load_lds_dwordx4 v[208:209], off
	v_lshl_add_u64 v[208:209], v[214:215], 0, s[90:91]
	s_mov_b32 m0, s29
	s_nop 0
	global_load_lds_dwordx4 v[208:209], off
	v_lshl_add_u64 v[208:209], v[222:223], 0, s[90:91]
	s_mov_b32 m0, s30
	s_nop 0
	global_load_lds_dwordx4 v[208:209], off
	s_waitcnt vmcnt(8)
	s_waitcnt lgkmcnt(0)
	s_barrier
	s_waitcnt lgkmcnt(0)
	v_mfma_f32_16x16x32_bf16 v[60:63], v[130:133], v[172:175], v[60:63]
	v_mfma_f32_16x16x32_bf16 v[56:59], v[138:141], v[172:175], v[56:59]
	v_mfma_f32_16x16x32_bf16 v[44:47], v[130:133], v[180:183], v[44:47]
	v_mfma_f32_16x16x32_bf16 v[40:43], v[138:141], v[180:183], v[40:43]
	v_mfma_f32_16x16x32_bf16 v[28:31], v[130:133], v[188:191], v[28:31]
	v_mfma_f32_16x16x32_bf16 v[24:27], v[138:141], v[188:191], v[24:27]
	v_mfma_f32_16x16x32_bf16 v[12:15], v[130:133], v[196:199], v[12:15]
	v_mfma_f32_16x16x32_bf16 v[8:11], v[138:141], v[196:199], v[8:11]
	v_mfma_f32_16x16x32_bf16 v[60:63], v[134:137], v[176:179], v[60:63]
	v_mfma_f32_16x16x32_bf16 v[56:59], v[142:145], v[176:179], v[56:59]
	v_mfma_f32_16x16x32_bf16 v[44:47], v[134:137], v[184:187], v[44:47]
	v_mfma_f32_16x16x32_bf16 v[40:43], v[142:145], v[184:187], v[40:43]
	v_mfma_f32_16x16x32_bf16 v[28:31], v[134:137], v[192:195], v[28:31]
	v_mfma_f32_16x16x32_bf16 v[24:27], v[142:145], v[192:195], v[24:27]
	v_mfma_f32_16x16x32_bf16 v[12:15], v[134:137], v[204:207], v[12:15]
	v_mfma_f32_16x16x32_bf16 v[8:11], v[142:145], v[204:207], v[8:11]
	v_mfma_f32_16x16x32_bf16 v[52:55], v[156:159], v[172:175], v[52:55]
	v_mfma_f32_16x16x32_bf16 v[48:51], v[164:167], v[172:175], v[48:51]
	v_mfma_f32_16x16x32_bf16 v[36:39], v[156:159], v[180:183], v[36:39]
	v_mfma_f32_16x16x32_bf16 v[32:35], v[164:167], v[180:183], v[32:35]
	v_mfma_f32_16x16x32_bf16 v[20:23], v[156:159], v[188:191], v[20:23]
	v_mfma_f32_16x16x32_bf16 v[16:19], v[164:167], v[188:191], v[16:19]
	v_mfma_f32_16x16x32_bf16 v[4:7], v[156:159], v[196:199], v[4:7]
	v_mfma_f32_16x16x32_bf16 v[0:3], v[164:167], v[196:199], v[0:3]
	v_mfma_f32_16x16x32_bf16 v[52:55], v[160:163], v[176:179], v[52:55]
	v_mfma_f32_16x16x32_bf16 v[48:51], v[168:171], v[176:179], v[48:51]
	v_mfma_f32_16x16x32_bf16 v[36:39], v[160:163], v[184:187], v[36:39]
	v_mfma_f32_16x16x32_bf16 v[32:35], v[168:171], v[184:187], v[32:35]
	s_setprio 1
	v_mfma_f32_16x16x32_bf16 v[20:23], v[160:163], v[192:195], v[20:23]
	v_mfma_f32_16x16x32_bf16 v[16:19], v[168:171], v[192:195], v[16:19]
	v_mfma_f32_16x16x32_bf16 v[4:7], v[160:163], v[204:207], v[4:7]
	s_barrier
	v_mfma_f32_16x16x32_bf16 v[0:3], v[168:171], v[204:207], v[0:3]
	s_setprio 0
	s_add_i32 s84, s84, 2
	s_add_u32 s36, s36, 0x100
	s_addc_u32 s37, s37, 0
	s_cmp_gt_u32 s84, 41
	s_mov_b64 s[96:97], s[42:43]
	s_cbranch_scc0 .LBB0_995
	s_and_b64 vcc, exec, s[62:63]
	s_cbranch_vccz .LBB0_998
	s_barrier
